# v24 plus: redundant lgkmcnt waits in the stats preludes removed, gate-up alignment barrier moved behind the first epilogue block of the leading half
# baseline (speedup 1.0000x reference)
.LBB0_292:
	s_lshl_b32 s18, s77, 11
	s_and_b32 s18, s18, 0x800
	s_add_i32 s18, s18, 0
	s_add_i32 s18, s18, 0x20000
	s_lshl_b32 s19, s57, 2
	s_add_i32 s19, s18, s19
	v_lshl_add_u32 v138, v159, 2, s19
	ds_read_b128 v[134:137], v138 offset:1024
	ds_read_b128 v[150:153], v138 offset:1040
	ds_read_b128 v[168:171], v138 offset:1536
	ds_read_b128 v[172:175], v138 offset:1552
	s_lshl_b32 s19, s56, 2
	s_add_i32 s18, s18, s19
	v_lshl_add_u32 v167, v157, 2, s18
	s_waitcnt lgkmcnt(0)
	v_pk_mul_f32 v[138:139], v[136:137], v[170:171]
	ds_read_b32 v170, v167
	v_cvt_f32_i32_e32 v125, v125
	v_cvt_f32_i32_e32 v124, v124
	v_cvt_f32_i32_e32 v123, v123
	v_cvt_f32_i32_e32 v122, v122
	v_cvt_f32_i32_e32 v129, v129
	v_cvt_f32_i32_e32 v128, v128
	v_cvt_f32_i32_e32 v127, v127
	v_cvt_f32_i32_e32 v126, v126
	v_cvt_f32_i32_e32 v119, v119
	v_cvt_f32_i32_e32 v118, v118
	v_cvt_f32_i32_e32 v121, v121
	v_cvt_f32_i32_e32 v120, v120
	v_cvt_f32_i32_e32 v115, v115
	v_cvt_f32_i32_e32 v114, v114
	v_cvt_f32_i32_e32 v117, v117
	v_cvt_f32_i32_e32 v116, v116
	v_lshl_add_u32 v166, s76, 8, v158
	v_lshl_or_b32 v176, s67, 7, v160
	s_mov_b32 s76, 0xbfb8aa3b
	v_pk_mul_f32 v[146:147], v[152:153], s[76:77] op_sel_hi:[1,0]
	v_pk_mul_f32 v[148:149], v[150:151], s[76:77] op_sel_hi:[1,0]
	v_ashrrev_i32_e32 v177, 31, v176
	s_waitcnt lgkmcnt(0)
	v_pk_mul_f32 v[122:123], v[170:171], v[122:123] op_sel_hi:[0,1]
	v_pk_mul_f32 v[124:125], v[170:171], v[124:125] op_sel_hi:[0,1]
	v_pk_mul_f32 v[142:143], v[136:137], s[76:77] op_sel_hi:[1,0]
	v_pk_mul_f32 v[144:145], v[134:135], s[76:77] op_sel_hi:[1,0]
	v_pk_mul_f32 v[140:141], v[134:135], v[168:169]
	v_pk_mul_f32 v[134:135], v[152:153], v[174:175]
	v_lshlrev_b64 v[152:153], 1, v[176:177]
	v_pk_mul_f32 v[126:127], v[170:171], v[126:127] op_sel_hi:[0,1]
	v_pk_mul_f32 v[128:129], v[170:171], v[128:129] op_sel_hi:[0,1]
	v_pk_mul_f32 v[174:175], v[146:147], v[124:125]
	v_pk_mul_f32 v[176:177], v[148:149], v[122:123]
	v_pk_mul_f32 v[136:137], v[150:151], v[172:173]
	v_pk_mul_f32 v[120:121], v[170:171], v[120:121] op_sel_hi:[0,1]
	v_pk_mul_f32 v[118:119], v[170:171], v[118:119] op_sel_hi:[0,1]
	v_pk_mul_f32 v[116:117], v[170:171], v[116:117] op_sel_hi:[0,1]
	v_pk_mul_f32 v[114:115], v[170:171], v[114:115] op_sel_hi:[0,1]
	v_pk_mul_f32 v[170:171], v[142:143], v[128:129]
	v_pk_mul_f32 v[172:173], v[144:145], v[126:127]
	v_exp_f32_e32 v176, v176
	v_exp_f32_e32 v177, v177
	v_exp_f32_e32 v174, v174
	v_exp_f32_e32 v175, v175
	v_exp_f32_e32 v172, v172
	v_exp_f32_e32 v173, v173
	v_exp_f32_e32 v170, v170
	v_exp_f32_e32 v171, v171
	v_pk_add_f32 v[174:175], v[174:175], 1.0 op_sel_hi:[1,0]
	v_pk_add_f32 v[176:177], v[176:177], 1.0 op_sel_hi:[1,0]
	v_pk_add_f32 v[172:173], v[172:173], 1.0 op_sel_hi:[1,0]
	v_pk_add_f32 v[170:171], v[170:171], 1.0 op_sel_hi:[1,0]
	v_rcp_f32_e32 v176, v176
	v_rcp_f32_e32 v177, v177
	v_rcp_f32_e32 v174, v174
	v_rcp_f32_e32 v175, v175
	v_rcp_f32_e32 v172, v172
	v_rcp_f32_e32 v173, v173
	v_rcp_f32_e32 v170, v170
	v_rcp_f32_e32 v171, v171
	v_mov_b64_e32 v[150:151], s[14:15]
	v_pk_mul_f32 v[114:115], v[122:123], v[114:115]
	v_pk_mul_f32 v[116:117], v[124:125], v[116:117]
	v_pk_mul_f32 v[122:123], v[136:137], v[176:177]
	v_pk_mul_f32 v[124:125], v[134:135], v[174:175]
	v_mad_i64_i32 v[168:169], s[18:19], v166, s87, v[150:151]
	v_pk_mul_f32 v[118:119], v[126:127], v[118:119]
	v_pk_mul_f32 v[120:121], v[128:129], v[120:121]
	v_pk_mul_f32 v[126:127], v[140:141], v[172:173]
	v_pk_mul_f32 v[128:129], v[138:139], v[170:171]
	v_pk_mul_f32 v[124:125], v[116:117], v[124:125]
	v_pk_mul_f32 v[116:117], v[114:115], v[122:123]
	v_lshl_add_u64 v[168:169], v[168:169], 0, v[152:153]
	v_mov_b64_e32 v[210:211], v[168:169]
	v_pk_mul_f32 v[120:121], v[120:121], v[128:129]
	v_pk_mul_f32 v[118:119], v[118:119], v[126:127]
	v_cvt_f32_i32_e32 v109, v109
	v_cvt_pk_bf16_f32 v114, v118, v119
	v_cvt_pk_bf16_f32 v115, v120, v121
	v_cvt_pk_bf16_f32 v116, v116, v117
	v_cvt_pk_bf16_f32 v117, v124, v125
	global_store_dwordx4 v[168:169], v[114:117], off
	s_and_b64 vcc, exec, s[16:17]
	s_cbranch_vccz .Lalign_skip_gu
	s_barrier
.Lalign_skip_gu:
	ds_read_b32 v116, v167 offset:64
	v_cvt_f32_i32_e32 v108, v108
	v_cvt_f32_i32_e32 v107, v107
	v_cvt_f32_i32_e32 v106, v106
	v_cvt_f32_i32_e32 v113, v113
	v_cvt_f32_i32_e32 v112, v112
	v_cvt_f32_i32_e32 v111, v111
	v_cvt_f32_i32_e32 v110, v110
	v_cvt_f32_i32_e32 v103, v103
	v_cvt_f32_i32_e32 v102, v102
	v_cvt_f32_i32_e32 v105, v105
	v_cvt_f32_i32_e32 v104, v104
	v_cvt_f32_i32_e32 v99, v99
	v_cvt_f32_i32_e32 v98, v98
	v_cvt_f32_i32_e32 v101, v101
	v_cvt_f32_i32_e32 v100, v100
	s_waitcnt lgkmcnt(0)
	v_pk_mul_f32 v[106:107], v[116:117], v[106:107] op_sel_hi:[0,1]
	v_pk_mul_f32 v[108:109], v[116:117], v[108:109] op_sel_hi:[0,1]
	v_pk_mul_f32 v[110:111], v[116:117], v[110:111] op_sel_hi:[0,1]
	v_pk_mul_f32 v[112:113], v[116:117], v[112:113] op_sel_hi:[0,1]
	v_pk_mul_f32 v[120:121], v[146:147], v[108:109]
	v_pk_mul_f32 v[122:123], v[148:149], v[106:107]
	v_pk_mul_f32 v[104:105], v[116:117], v[104:105] op_sel_hi:[0,1]
	v_pk_mul_f32 v[102:103], v[116:117], v[102:103] op_sel_hi:[0,1]
	v_pk_mul_f32 v[100:101], v[116:117], v[100:101] op_sel_hi:[0,1]
	v_pk_mul_f32 v[98:99], v[116:117], v[98:99] op_sel_hi:[0,1]
	v_pk_mul_f32 v[116:117], v[142:143], v[112:113]
	v_pk_mul_f32 v[118:119], v[144:145], v[110:111]
	v_exp_f32_e32 v122, v122
	v_exp_f32_e32 v123, v123
	v_exp_f32_e32 v120, v120
	v_exp_f32_e32 v121, v121
	v_exp_f32_e32 v118, v118
	v_exp_f32_e32 v119, v119
	v_exp_f32_e32 v116, v116
	v_exp_f32_e32 v117, v117
	v_pk_add_f32 v[120:121], v[120:121], 1.0 op_sel_hi:[1,0]
	v_pk_add_f32 v[122:123], v[122:123], 1.0 op_sel_hi:[1,0]
	v_pk_add_f32 v[118:119], v[118:119], 1.0 op_sel_hi:[1,0]
	v_pk_add_f32 v[116:117], v[116:117], 1.0 op_sel_hi:[1,0]
	v_rcp_f32_e32 v122, v122
	v_rcp_f32_e32 v123, v123
	v_rcp_f32_e32 v120, v120
	v_rcp_f32_e32 v121, v121
	v_rcp_f32_e32 v118, v118
	v_rcp_f32_e32 v119, v119
	v_rcp_f32_e32 v116, v116
	v_rcp_f32_e32 v117, v117
	s_mov_b32 s98, 0x2c000
	v_pk_mul_f32 v[98:99], v[106:107], v[98:99]
	v_pk_mul_f32 v[100:101], v[108:109], v[100:101]
	v_pk_mul_f32 v[106:107], v[136:137], v[122:123]
	v_pk_mul_f32 v[108:109], v[134:135], v[120:121]
	s_mov_b32 s99, 0
	v_pk_mul_f32 v[102:103], v[110:111], v[102:103]
	v_pk_mul_f32 v[104:105], v[112:113], v[104:105]
	v_pk_mul_f32 v[110:111], v[140:141], v[118:119]
	v_pk_mul_f32 v[112:113], v[138:139], v[116:117]
	v_pk_mul_f32 v[108:109], v[100:101], v[108:109]
	v_pk_mul_f32 v[100:101], v[98:99], v[106:107]
	v_lshl_add_u64 v[114:115], v[210:211], 0, s[98:99]
	v_pk_mul_f32 v[104:105], v[104:105], v[112:113]
	v_pk_mul_f32 v[102:103], v[102:103], v[110:111]
	v_cvt_f32_i32_e32 v93, v93
	v_cvt_pk_bf16_f32 v98, v102, v103
	v_cvt_pk_bf16_f32 v99, v104, v105
	v_cvt_pk_bf16_f32 v100, v100, v101
	v_cvt_pk_bf16_f32 v101, v108, v109
	global_store_dwordx4 v[114:115], v[98:101], off
	ds_read_b32 v100, v167 offset:128
	v_cvt_f32_i32_e32 v92, v92
	v_cvt_f32_i32_e32 v91, v91
	v_cvt_f32_i32_e32 v90, v90
	v_cvt_f32_i32_e32 v97, v97
	v_cvt_f32_i32_e32 v96, v96
	v_cvt_f32_i32_e32 v95, v95
	v_cvt_f32_i32_e32 v94, v94
	v_cvt_f32_i32_e32 v87, v87
	v_cvt_f32_i32_e32 v86, v86
	v_cvt_f32_i32_e32 v89, v89
	v_cvt_f32_i32_e32 v88, v88
	v_cvt_f32_i32_e32 v83, v83
	v_cvt_f32_i32_e32 v82, v82
	v_cvt_f32_i32_e32 v85, v85
	v_cvt_f32_i32_e32 v84, v84
	s_waitcnt lgkmcnt(0)
	v_pk_mul_f32 v[90:91], v[100:101], v[90:91] op_sel_hi:[0,1]
	v_pk_mul_f32 v[92:93], v[100:101], v[92:93] op_sel_hi:[0,1]
	v_pk_mul_f32 v[94:95], v[100:101], v[94:95] op_sel_hi:[0,1]
	v_pk_mul_f32 v[96:97], v[100:101], v[96:97] op_sel_hi:[0,1]
	v_pk_mul_f32 v[104:105], v[146:147], v[92:93]
	v_pk_mul_f32 v[106:107], v[148:149], v[90:91]
	v_pk_mul_f32 v[88:89], v[100:101], v[88:89] op_sel_hi:[0,1]
	v_pk_mul_f32 v[86:87], v[100:101], v[86:87] op_sel_hi:[0,1]
	v_pk_mul_f32 v[84:85], v[100:101], v[84:85] op_sel_hi:[0,1]
	v_pk_mul_f32 v[82:83], v[100:101], v[82:83] op_sel_hi:[0,1]
	v_pk_mul_f32 v[100:101], v[142:143], v[96:97]
	v_pk_mul_f32 v[102:103], v[144:145], v[94:95]
	v_exp_f32_e32 v106, v106
	v_exp_f32_e32 v107, v107
	v_exp_f32_e32 v104, v104
	v_exp_f32_e32 v105, v105
	v_exp_f32_e32 v102, v102
	v_exp_f32_e32 v103, v103
	v_exp_f32_e32 v100, v100
	v_exp_f32_e32 v101, v101
	v_pk_add_f32 v[104:105], v[104:105], 1.0 op_sel_hi:[1,0]
	v_pk_add_f32 v[106:107], v[106:107], 1.0 op_sel_hi:[1,0]
	v_pk_add_f32 v[102:103], v[102:103], 1.0 op_sel_hi:[1,0]
	v_pk_add_f32 v[100:101], v[100:101], 1.0 op_sel_hi:[1,0]
	v_rcp_f32_e32 v106, v106
	v_rcp_f32_e32 v107, v107
	v_rcp_f32_e32 v104, v104
	v_rcp_f32_e32 v105, v105
	v_rcp_f32_e32 v102, v102
	v_rcp_f32_e32 v103, v103
	v_rcp_f32_e32 v100, v100
	v_rcp_f32_e32 v101, v101
	s_mov_b32 s98, 0x58000
	v_pk_mul_f32 v[82:83], v[90:91], v[82:83]
	v_pk_mul_f32 v[84:85], v[92:93], v[84:85]
	v_pk_mul_f32 v[90:91], v[136:137], v[106:107]
	v_pk_mul_f32 v[92:93], v[134:135], v[104:105]
	s_mov_b32 s99, 0
	v_pk_mul_f32 v[86:87], v[94:95], v[86:87]
	v_pk_mul_f32 v[88:89], v[96:97], v[88:89]
	v_pk_mul_f32 v[94:95], v[140:141], v[102:103]
	v_pk_mul_f32 v[96:97], v[138:139], v[100:101]
	v_pk_mul_f32 v[92:93], v[84:85], v[92:93]
	v_pk_mul_f32 v[84:85], v[82:83], v[90:91]
	v_lshl_add_u64 v[98:99], v[210:211], 0, s[98:99]
	v_pk_mul_f32 v[88:89], v[88:89], v[96:97]
	v_pk_mul_f32 v[86:87], v[86:87], v[94:95]
	v_cvt_f32_i32_e32 v77, v77
	v_cvt_pk_bf16_f32 v82, v86, v87
	v_cvt_pk_bf16_f32 v83, v88, v89
	v_cvt_pk_bf16_f32 v84, v84, v85
	v_cvt_pk_bf16_f32 v85, v92, v93
	global_store_dwordx4 v[98:99], v[82:85], off
	ds_read_b32 v84, v167 offset:192
	v_cvt_f32_i32_e32 v76, v76
	v_cvt_f32_i32_e32 v75, v75
	v_cvt_f32_i32_e32 v74, v74
	v_cvt_f32_i32_e32 v81, v81
	v_cvt_f32_i32_e32 v80, v80
	v_cvt_f32_i32_e32 v79, v79
	v_cvt_f32_i32_e32 v78, v78
	v_cvt_f32_i32_e32 v71, v71
	v_cvt_f32_i32_e32 v70, v70
	v_cvt_f32_i32_e32 v73, v73
	v_cvt_f32_i32_e32 v72, v72
	v_cvt_f32_i32_e32 v67, v67
	v_cvt_f32_i32_e32 v66, v66
	v_cvt_f32_i32_e32 v69, v69
	v_cvt_f32_i32_e32 v68, v68
	s_waitcnt lgkmcnt(0)
	v_pk_mul_f32 v[74:75], v[84:85], v[74:75] op_sel_hi:[0,1]
	v_pk_mul_f32 v[76:77], v[84:85], v[76:77] op_sel_hi:[0,1]
	v_pk_mul_f32 v[78:79], v[84:85], v[78:79] op_sel_hi:[0,1]
	v_pk_mul_f32 v[80:81], v[84:85], v[80:81] op_sel_hi:[0,1]
	v_pk_mul_f32 v[88:89], v[146:147], v[76:77]
	v_pk_mul_f32 v[90:91], v[148:149], v[74:75]
	v_pk_mul_f32 v[72:73], v[84:85], v[72:73] op_sel_hi:[0,1]
	v_pk_mul_f32 v[70:71], v[84:85], v[70:71] op_sel_hi:[0,1]
	v_pk_mul_f32 v[68:69], v[84:85], v[68:69] op_sel_hi:[0,1]
	v_pk_mul_f32 v[66:67], v[84:85], v[66:67] op_sel_hi:[0,1]
	v_pk_mul_f32 v[84:85], v[142:143], v[80:81]
	v_pk_mul_f32 v[86:87], v[144:145], v[78:79]
	v_exp_f32_e32 v90, v90
	v_exp_f32_e32 v91, v91
	v_exp_f32_e32 v88, v88
	v_exp_f32_e32 v89, v89
	v_exp_f32_e32 v86, v86
	v_exp_f32_e32 v87, v87
	v_exp_f32_e32 v84, v84
	v_exp_f32_e32 v85, v85
	v_pk_add_f32 v[88:89], v[88:89], 1.0 op_sel_hi:[1,0]
	v_pk_add_f32 v[90:91], v[90:91], 1.0 op_sel_hi:[1,0]
	v_pk_add_f32 v[86:87], v[86:87], 1.0 op_sel_hi:[1,0]
	v_pk_add_f32 v[84:85], v[84:85], 1.0 op_sel_hi:[1,0]
	v_rcp_f32_e32 v90, v90
	v_rcp_f32_e32 v91, v91
	v_rcp_f32_e32 v88, v88
	v_rcp_f32_e32 v89, v89
	v_rcp_f32_e32 v86, v86
	v_rcp_f32_e32 v87, v87
	v_rcp_f32_e32 v84, v84
	v_rcp_f32_e32 v85, v85
	s_mov_b32 s98, 0x84000
	v_pk_mul_f32 v[66:67], v[74:75], v[66:67]
	v_pk_mul_f32 v[68:69], v[76:77], v[68:69]
	v_pk_mul_f32 v[74:75], v[136:137], v[90:91]
	v_pk_mul_f32 v[76:77], v[134:135], v[88:89]
	s_mov_b32 s99, 0
	v_pk_mul_f32 v[70:71], v[78:79], v[70:71]
	v_pk_mul_f32 v[72:73], v[80:81], v[72:73]
	v_pk_mul_f32 v[78:79], v[140:141], v[86:87]
	v_pk_mul_f32 v[80:81], v[138:139], v[84:85]
	v_pk_mul_f32 v[76:77], v[68:69], v[76:77]
	v_pk_mul_f32 v[68:69], v[66:67], v[74:75]
	v_lshl_add_u64 v[82:83], v[210:211], 0, s[98:99]
	v_pk_mul_f32 v[72:73], v[72:73], v[80:81]
	v_pk_mul_f32 v[70:71], v[70:71], v[78:79]
	v_cvt_f32_i32_e32 v61, v61
	v_cvt_pk_bf16_f32 v66, v70, v71
	v_cvt_pk_bf16_f32 v67, v72, v73
	v_cvt_pk_bf16_f32 v68, v68, v69
	v_cvt_pk_bf16_f32 v69, v76, v77
	global_store_dwordx4 v[82:83], v[66:69], off
	ds_read_b32 v68, v167 offset:512
	v_cvt_f32_i32_e32 v60, v60
	v_cvt_f32_i32_e32 v59, v59
	v_cvt_f32_i32_e32 v58, v58
	v_cvt_f32_i32_e32 v65, v65
	v_cvt_f32_i32_e32 v64, v64
	v_cvt_f32_i32_e32 v63, v63
	v_cvt_f32_i32_e32 v62, v62
	v_cvt_f32_i32_e32 v55, v55
	v_cvt_f32_i32_e32 v54, v54
	v_cvt_f32_i32_e32 v57, v57
	v_cvt_f32_i32_e32 v56, v56
	v_cvt_f32_i32_e32 v51, v51
	v_cvt_f32_i32_e32 v50, v50
	v_cvt_f32_i32_e32 v53, v53
	v_cvt_f32_i32_e32 v52, v52
	s_waitcnt lgkmcnt(0)
	v_pk_mul_f32 v[58:59], v[68:69], v[58:59] op_sel_hi:[0,1]
	v_pk_mul_f32 v[60:61], v[68:69], v[60:61] op_sel_hi:[0,1]
	v_pk_mul_f32 v[62:63], v[68:69], v[62:63] op_sel_hi:[0,1]
	v_pk_mul_f32 v[64:65], v[68:69], v[64:65] op_sel_hi:[0,1]
	v_pk_mul_f32 v[72:73], v[146:147], v[60:61]
	v_pk_mul_f32 v[74:75], v[148:149], v[58:59]
	v_pk_mul_f32 v[56:57], v[68:69], v[56:57] op_sel_hi:[0,1]
	v_pk_mul_f32 v[54:55], v[68:69], v[54:55] op_sel_hi:[0,1]
	v_pk_mul_f32 v[52:53], v[68:69], v[52:53] op_sel_hi:[0,1]
	v_pk_mul_f32 v[50:51], v[68:69], v[50:51] op_sel_hi:[0,1]
	v_pk_mul_f32 v[68:69], v[142:143], v[64:65]
	v_pk_mul_f32 v[70:71], v[144:145], v[62:63]
	v_exp_f32_e32 v74, v74
	v_exp_f32_e32 v75, v75
	v_exp_f32_e32 v72, v72
	v_exp_f32_e32 v73, v73
	v_exp_f32_e32 v70, v70
	v_exp_f32_e32 v71, v71
	v_exp_f32_e32 v68, v68
	v_exp_f32_e32 v69, v69
	v_pk_add_f32 v[72:73], v[72:73], 1.0 op_sel_hi:[1,0]
	v_pk_add_f32 v[74:75], v[74:75], 1.0 op_sel_hi:[1,0]
	v_pk_add_f32 v[70:71], v[70:71], 1.0 op_sel_hi:[1,0]
	v_pk_add_f32 v[68:69], v[68:69], 1.0 op_sel_hi:[1,0]
	v_rcp_f32_e32 v74, v74
	v_rcp_f32_e32 v75, v75
	v_rcp_f32_e32 v72, v72
	v_rcp_f32_e32 v73, v73
	v_rcp_f32_e32 v70, v70
	v_rcp_f32_e32 v71, v71
	v_rcp_f32_e32 v68, v68
	v_rcp_f32_e32 v69, v69
	s_mov_b32 s98, 0x160000
	v_pk_mul_f32 v[50:51], v[58:59], v[50:51]
	v_pk_mul_f32 v[52:53], v[60:61], v[52:53]
	v_pk_mul_f32 v[58:59], v[136:137], v[74:75]
	v_pk_mul_f32 v[60:61], v[134:135], v[72:73]
	s_mov_b32 s99, 0
	v_pk_mul_f32 v[54:55], v[62:63], v[54:55]
	v_pk_mul_f32 v[56:57], v[64:65], v[56:57]
	v_pk_mul_f32 v[62:63], v[140:141], v[70:71]
	v_pk_mul_f32 v[64:65], v[138:139], v[68:69]
	v_pk_mul_f32 v[60:61], v[52:53], v[60:61]
	v_pk_mul_f32 v[52:53], v[50:51], v[58:59]
	v_lshl_add_u64 v[66:67], v[210:211], 0, s[98:99]
	v_pk_mul_f32 v[56:57], v[56:57], v[64:65]
	v_pk_mul_f32 v[54:55], v[54:55], v[62:63]
	v_cvt_f32_i32_e32 v45, v45
	v_cvt_pk_bf16_f32 v50, v54, v55
	v_cvt_pk_bf16_f32 v51, v56, v57
	v_cvt_pk_bf16_f32 v52, v52, v53
	v_cvt_pk_bf16_f32 v53, v60, v61
	global_store_dwordx4 v[66:67], v[50:53], off
	ds_read_b32 v52, v167 offset:576
	v_cvt_f32_i32_e32 v44, v44
	v_cvt_f32_i32_e32 v43, v43
	v_cvt_f32_i32_e32 v42, v42
	v_cvt_f32_i32_e32 v49, v49
	v_cvt_f32_i32_e32 v48, v48
	v_cvt_f32_i32_e32 v47, v47
	v_cvt_f32_i32_e32 v46, v46
	v_cvt_f32_i32_e32 v39, v39
	v_cvt_f32_i32_e32 v38, v38
	v_cvt_f32_i32_e32 v41, v41
	v_cvt_f32_i32_e32 v40, v40
	v_cvt_f32_i32_e32 v35, v35
	v_cvt_f32_i32_e32 v34, v34
	v_cvt_f32_i32_e32 v37, v37
	v_cvt_f32_i32_e32 v36, v36
	s_waitcnt lgkmcnt(0)
	v_pk_mul_f32 v[42:43], v[52:53], v[42:43] op_sel_hi:[0,1]
	v_pk_mul_f32 v[44:45], v[52:53], v[44:45] op_sel_hi:[0,1]
	v_pk_mul_f32 v[46:47], v[52:53], v[46:47] op_sel_hi:[0,1]
	v_pk_mul_f32 v[48:49], v[52:53], v[48:49] op_sel_hi:[0,1]
	v_pk_mul_f32 v[56:57], v[146:147], v[44:45]
	v_pk_mul_f32 v[58:59], v[148:149], v[42:43]
	v_pk_mul_f32 v[40:41], v[52:53], v[40:41] op_sel_hi:[0,1]
	v_pk_mul_f32 v[38:39], v[52:53], v[38:39] op_sel_hi:[0,1]
	v_pk_mul_f32 v[36:37], v[52:53], v[36:37] op_sel_hi:[0,1]
	v_pk_mul_f32 v[34:35], v[52:53], v[34:35] op_sel_hi:[0,1]
	v_pk_mul_f32 v[52:53], v[142:143], v[48:49]
	v_pk_mul_f32 v[54:55], v[144:145], v[46:47]
	v_exp_f32_e32 v58, v58
	v_exp_f32_e32 v59, v59
	v_exp_f32_e32 v56, v56
	v_exp_f32_e32 v57, v57
	v_exp_f32_e32 v54, v54
	v_exp_f32_e32 v55, v55
	v_exp_f32_e32 v52, v52
	v_exp_f32_e32 v53, v53
	v_pk_add_f32 v[56:57], v[56:57], 1.0 op_sel_hi:[1,0]
	v_pk_add_f32 v[58:59], v[58:59], 1.0 op_sel_hi:[1,0]
	v_pk_add_f32 v[54:55], v[54:55], 1.0 op_sel_hi:[1,0]
	v_pk_add_f32 v[52:53], v[52:53], 1.0 op_sel_hi:[1,0]
	v_rcp_f32_e32 v58, v58
	v_rcp_f32_e32 v59, v59
	v_rcp_f32_e32 v56, v56
	v_rcp_f32_e32 v57, v57
	v_rcp_f32_e32 v54, v54
	v_rcp_f32_e32 v55, v55
	v_rcp_f32_e32 v52, v52
	v_rcp_f32_e32 v53, v53
	s_mov_b32 s98, 0x18c000
	v_pk_mul_f32 v[34:35], v[42:43], v[34:35]
	v_pk_mul_f32 v[36:37], v[44:45], v[36:37]
	v_pk_mul_f32 v[42:43], v[136:137], v[58:59]
	v_pk_mul_f32 v[44:45], v[134:135], v[56:57]
	s_mov_b32 s99, 0
	v_pk_mul_f32 v[38:39], v[46:47], v[38:39]
	v_pk_mul_f32 v[40:41], v[48:49], v[40:41]
	v_pk_mul_f32 v[46:47], v[140:141], v[54:55]
	v_pk_mul_f32 v[48:49], v[138:139], v[52:53]
	v_pk_mul_f32 v[44:45], v[36:37], v[44:45]
	v_pk_mul_f32 v[36:37], v[34:35], v[42:43]
	v_lshl_add_u64 v[50:51], v[210:211], 0, s[98:99]
	v_pk_mul_f32 v[40:41], v[40:41], v[48:49]
	v_pk_mul_f32 v[38:39], v[38:39], v[46:47]
	v_cvt_f32_i32_e32 v29, v29
	v_cvt_pk_bf16_f32 v34, v38, v39
	v_cvt_pk_bf16_f32 v35, v40, v41
	v_cvt_pk_bf16_f32 v36, v36, v37
	v_cvt_pk_bf16_f32 v37, v44, v45
	global_store_dwordx4 v[50:51], v[34:37], off
	ds_read_b32 v36, v167 offset:640
	v_cvt_f32_i32_e32 v28, v28
	v_cvt_f32_i32_e32 v27, v27
	v_cvt_f32_i32_e32 v26, v26
	v_cvt_f32_i32_e32 v33, v33
	v_cvt_f32_i32_e32 v32, v32
	v_cvt_f32_i32_e32 v31, v31
	v_cvt_f32_i32_e32 v30, v30
	v_cvt_f32_i32_e32 v23, v23
	v_cvt_f32_i32_e32 v22, v22
	v_cvt_f32_i32_e32 v25, v25
	v_cvt_f32_i32_e32 v24, v24
	v_cvt_f32_i32_e32 v19, v19
	v_cvt_f32_i32_e32 v18, v18
	v_cvt_f32_i32_e32 v21, v21
	v_cvt_f32_i32_e32 v20, v20
	s_waitcnt lgkmcnt(0)
	v_pk_mul_f32 v[26:27], v[36:37], v[26:27] op_sel_hi:[0,1]
	v_pk_mul_f32 v[28:29], v[36:37], v[28:29] op_sel_hi:[0,1]
	v_pk_mul_f32 v[30:31], v[36:37], v[30:31] op_sel_hi:[0,1]
	v_pk_mul_f32 v[32:33], v[36:37], v[32:33] op_sel_hi:[0,1]
	v_pk_mul_f32 v[40:41], v[146:147], v[28:29]
	v_pk_mul_f32 v[42:43], v[148:149], v[26:27]
	v_pk_mul_f32 v[24:25], v[36:37], v[24:25] op_sel_hi:[0,1]
	v_pk_mul_f32 v[22:23], v[36:37], v[22:23] op_sel_hi:[0,1]
	v_pk_mul_f32 v[20:21], v[36:37], v[20:21] op_sel_hi:[0,1]
	v_pk_mul_f32 v[18:19], v[36:37], v[18:19] op_sel_hi:[0,1]
	v_pk_mul_f32 v[36:37], v[142:143], v[32:33]
	v_pk_mul_f32 v[38:39], v[144:145], v[30:31]
	v_exp_f32_e32 v42, v42
	v_exp_f32_e32 v43, v43
	v_exp_f32_e32 v40, v40
	v_exp_f32_e32 v41, v41
	v_exp_f32_e32 v38, v38
	v_exp_f32_e32 v39, v39
	v_exp_f32_e32 v36, v36
	v_exp_f32_e32 v37, v37
	v_pk_add_f32 v[40:41], v[40:41], 1.0 op_sel_hi:[1,0]
	v_pk_add_f32 v[42:43], v[42:43], 1.0 op_sel_hi:[1,0]
	v_pk_add_f32 v[38:39], v[38:39], 1.0 op_sel_hi:[1,0]
	v_pk_add_f32 v[36:37], v[36:37], 1.0 op_sel_hi:[1,0]
	v_rcp_f32_e32 v42, v42
	v_rcp_f32_e32 v43, v43
	v_rcp_f32_e32 v40, v40
	v_rcp_f32_e32 v41, v41
	v_rcp_f32_e32 v38, v38
	v_rcp_f32_e32 v39, v39
	v_rcp_f32_e32 v36, v36
	v_rcp_f32_e32 v37, v37
	s_mov_b32 s98, 0x1b8000
	v_pk_mul_f32 v[18:19], v[26:27], v[18:19]
	v_pk_mul_f32 v[20:21], v[28:29], v[20:21]
	v_pk_mul_f32 v[26:27], v[136:137], v[42:43]
	v_pk_mul_f32 v[28:29], v[134:135], v[40:41]
	s_mov_b32 s99, 0
	v_pk_mul_f32 v[22:23], v[30:31], v[22:23]
	v_pk_mul_f32 v[24:25], v[32:33], v[24:25]
	v_pk_mul_f32 v[30:31], v[140:141], v[38:39]
	v_pk_mul_f32 v[32:33], v[138:139], v[36:37]
	v_pk_mul_f32 v[28:29], v[20:21], v[28:29]
	v_pk_mul_f32 v[20:21], v[18:19], v[26:27]
	v_lshl_add_u64 v[34:35], v[210:211], 0, s[98:99]
	v_pk_mul_f32 v[24:25], v[24:25], v[32:33]
	v_pk_mul_f32 v[22:23], v[22:23], v[30:31]
	v_cvt_f32_i32_e32 v13, v13
	v_cvt_pk_bf16_f32 v18, v22, v23
	v_cvt_pk_bf16_f32 v19, v24, v25
	v_cvt_pk_bf16_f32 v20, v20, v21
	v_cvt_pk_bf16_f32 v21, v28, v29
	global_store_dwordx4 v[34:35], v[18:21], off
	ds_read_b32 v20, v167 offset:704
	v_cvt_f32_i32_e32 v12, v12
	v_cvt_f32_i32_e32 v11, v11
	v_cvt_f32_i32_e32 v10, v10
	v_cvt_f32_i32_e32 v17, v17
	v_cvt_f32_i32_e32 v16, v16
	v_cvt_f32_i32_e32 v15, v15
	v_cvt_f32_i32_e32 v14, v14
	v_cvt_f32_i32_e32 v7, v7
	v_cvt_f32_i32_e32 v6, v6
	v_cvt_f32_i32_e32 v9, v9
	v_cvt_f32_i32_e32 v8, v8
	v_cvt_f32_i32_e32 v3, v3
	v_cvt_f32_i32_e32 v2, v2
	v_cvt_f32_i32_e32 v5, v5
	v_cvt_f32_i32_e32 v4, v4
	s_waitcnt lgkmcnt(0)
	v_pk_mul_f32 v[10:11], v[20:21], v[10:11] op_sel_hi:[0,1]
	v_pk_mul_f32 v[12:13], v[20:21], v[12:13] op_sel_hi:[0,1]
	v_pk_mul_f32 v[14:15], v[20:21], v[14:15] op_sel_hi:[0,1]
	v_pk_mul_f32 v[16:17], v[20:21], v[16:17] op_sel_hi:[0,1]
	v_pk_mul_f32 v[24:25], v[146:147], v[12:13]
	v_pk_mul_f32 v[26:27], v[148:149], v[10:11]
	v_pk_mul_f32 v[8:9], v[20:21], v[8:9] op_sel_hi:[0,1]
	v_pk_mul_f32 v[6:7], v[20:21], v[6:7] op_sel_hi:[0,1]
	v_pk_mul_f32 v[4:5], v[20:21], v[4:5] op_sel_hi:[0,1]
	v_pk_mul_f32 v[2:3], v[20:21], v[2:3] op_sel_hi:[0,1]
	v_pk_mul_f32 v[20:21], v[142:143], v[16:17]
	v_pk_mul_f32 v[22:23], v[144:145], v[14:15]
	v_exp_f32_e32 v26, v26
	v_exp_f32_e32 v27, v27
	v_exp_f32_e32 v24, v24
	v_exp_f32_e32 v25, v25
	v_exp_f32_e32 v22, v22
	v_exp_f32_e32 v23, v23
	v_exp_f32_e32 v20, v20
	v_exp_f32_e32 v21, v21
	v_pk_add_f32 v[24:25], v[24:25], 1.0 op_sel_hi:[1,0]
	v_pk_add_f32 v[26:27], v[26:27], 1.0 op_sel_hi:[1,0]
	v_pk_add_f32 v[22:23], v[22:23], 1.0 op_sel_hi:[1,0]
	v_pk_add_f32 v[20:21], v[20:21], 1.0 op_sel_hi:[1,0]
	v_rcp_f32_e32 v26, v26
	v_rcp_f32_e32 v27, v27
	v_rcp_f32_e32 v24, v24
	v_rcp_f32_e32 v25, v25
	v_rcp_f32_e32 v22, v22
	v_rcp_f32_e32 v23, v23
	v_rcp_f32_e32 v20, v20
	v_rcp_f32_e32 v21, v21
	s_mov_b32 s98, 0x1e4000
	s_mov_b32 s99, 0
	v_pk_mul_f32 v[2:3], v[10:11], v[2:3]
	v_pk_mul_f32 v[4:5], v[12:13], v[4:5]
	v_pk_mul_f32 v[10:11], v[136:137], v[26:27]
	v_pk_mul_f32 v[12:13], v[134:135], v[24:25]
	v_lshl_add_u64 v[18:19], v[210:211], 0, s[98:99]
	v_pk_mul_f32 v[6:7], v[14:15], v[6:7]
	v_pk_mul_f32 v[8:9], v[16:17], v[8:9]
	v_pk_mul_f32 v[14:15], v[140:141], v[22:23]
	v_pk_mul_f32 v[16:17], v[138:139], v[20:21]
	v_pk_mul_f32 v[12:13], v[4:5], v[12:13]
	v_pk_mul_f32 v[4:5], v[2:3], v[10:11]
	s_mov_b64 s[18:19], -1
	s_andn2_b64 vcc, exec, s[8:9]
	v_pk_mul_f32 v[8:9], v[8:9], v[16:17]
	v_pk_mul_f32 v[6:7], v[6:7], v[14:15]
	s_nop 0
	v_cvt_pk_bf16_f32 v2, v6, v7
	v_cvt_pk_bf16_f32 v3, v8, v9
	v_cvt_pk_bf16_f32 v4, v4, v5
	v_cvt_pk_bf16_f32 v5, v12, v13
	global_store_dwordx4 v[18:19], v[2:5], off
	s_cbranch_vccnz .LBB0_285
	s_and_saveexec_b64 s[8:9], s[6:7]
	s_xor_b64 s[8:9], exec, s[8:9]
	s_lshl_b32 s18, s63, 8
	s_ashr_i32 s19, s18, 31
	v_lshl_add_u64 v[2:3], s[18:19], 2, v[130:131]
	s_movk_i32 s18, 0xfc00
	s_mov_b32 s19, -1
	v_lshl_add_u64 v[2:3], v[2:3], 0, s[18:19]
	s_andn2_saveexec_b64 s[8:9], s[8:9]
	s_lshl_b32 s18, s64, 8
	s_ashr_i32 s19, s18, 31
	v_lshl_add_u64 v[2:3], s[18:19], 2, v[132:133]
	s_or_b64 exec, exec, s[8:9]
	s_lshl_b32 s8, s62, 11
	s_and_b32 s8, s8, 0x800
	s_add_i32 m0, s23, s8
	s_andn2_b64 vcc, exec, s[12:13]
	global_load_lds_dword v[2:3], off
	s_cbranch_vccnz .LBB0_284
	s_barrier
	s_branch .LBB0_284

.LBB0_403:
	s_or_b64 exec, exec, s[10:11]
	v_mul_f32_e32 v212, v43, v43
	v_mul_f32_e32 v213, v45, v45
	v_fmac_f32_e32 v212, v42, v42
	v_fmac_f32_e32 v213, v44, v44
	v_add_f32_e32 v212, v212, v213
	v_mul_f32_e32 v213, v35, v35
	v_mul_f32_e32 v214, v37, v37
	v_fmac_f32_e32 v213, v34, v34
	v_fmac_f32_e32 v214, v36, v36
	v_add_f32_e32 v213, v213, v214
	v_add_f32_e32 v212, v212, v213
	v_mul_f32_e32 v213, v63, v63
	v_mul_f32_e32 v214, v65, v65
	v_fmac_f32_e32 v213, v62, v62
	v_fmac_f32_e32 v214, v64, v64
	v_add_f32_e32 v213, v213, v214
	v_add_f32_e32 v212, v212, v213
	v_mul_f32_e32 v213, v59, v59
	v_mul_f32_e32 v214, v61, v61
	v_fmac_f32_e32 v213, v58, v58
	v_fmac_f32_e32 v214, v60, v60
	v_add_f32_e32 v213, v213, v214
	v_add_f32_e32 v212, v212, v213
	v_mov_b32_e32 v213, v212
	s_nop 1
	v_permlane16_swap_b32_e32 v213, v212
	s_waitcnt lgkmcnt(0)
	v_add_f32_e32 v212, v212, v213
	v_mov_b32_e32 v213, v212
	s_nop 1
	v_permlane32_swap_b32_e32 v213, v212
	s_and_saveexec_b64 s[10:11], s[8:9]
	s_cbranch_execz .LBB0_405
	s_lshl_b32 s13, s57, 11
	s_add_i32 s13, s37, s13
	v_lshl_add_u32 v214, v219, 5, s13
	s_waitcnt lgkmcnt(0)
	v_add_f32_e32 v212, v212, v213
	v_mov_b32_e32 v213, v223
	ds_write_b64 v214, v[212:213] offset:512
.LBB0_405:
	s_or_b64 exec, exec, s[10:11]
	v_mul_f32_e32 v212, v55, v55
	v_mul_f32_e32 v213, v57, v57
	v_fmac_f32_e32 v212, v54, v54
	v_fmac_f32_e32 v213, v56, v56
	v_add_f32_e32 v212, v212, v213
	v_mul_f32_e32 v213, v51, v51
	v_mul_f32_e32 v214, v53, v53
	v_fmac_f32_e32 v213, v50, v50
	v_fmac_f32_e32 v214, v52, v52
	v_add_f32_e32 v213, v213, v214
	v_add_f32_e32 v212, v212, v213
	v_mul_f32_e32 v213, v87, v87
	v_mul_f32_e32 v214, v89, v89
	v_fmac_f32_e32 v213, v86, v86
	v_fmac_f32_e32 v214, v88, v88
	v_add_f32_e32 v213, v213, v214
	v_add_f32_e32 v212, v212, v213
	v_mul_f32_e32 v213, v83, v83
	v_mul_f32_e32 v214, v85, v85
	v_fmac_f32_e32 v213, v82, v82
	v_fmac_f32_e32 v214, v84, v84
	v_add_f32_e32 v213, v213, v214
	v_add_f32_e32 v212, v212, v213
	v_mov_b32_e32 v213, v212
	s_nop 1
	v_permlane16_swap_b32_e32 v213, v212
	s_waitcnt lgkmcnt(0)
	v_add_f32_e32 v212, v212, v213
	v_mov_b32_e32 v213, v212
	s_nop 1
	v_permlane32_swap_b32_e32 v213, v212
	s_and_saveexec_b64 s[10:11], s[8:9]
	s_cbranch_execz .LBB0_407
	s_lshl_b32 s13, s57, 11
	s_add_i32 s13, s37, s13
	v_lshl_add_u32 v214, v219, 5, s13
	s_waitcnt lgkmcnt(0)
	v_add_f32_e32 v212, v212, v213
	v_mov_b32_e32 v213, v223
	ds_write_b64 v214, v[212:213] offset:1024
.LBB0_407:
	s_or_b64 exec, exec, s[10:11]
	v_mul_f32_e32 v212, v79, v79
	v_mul_f32_e32 v213, v81, v81
	v_fmac_f32_e32 v212, v78, v78
	v_fmac_f32_e32 v213, v80, v80
	v_add_f32_e32 v212, v212, v213
	v_mul_f32_e32 v213, v71, v71
	v_mul_f32_e32 v214, v73, v73
	v_fmac_f32_e32 v213, v70, v70
	v_fmac_f32_e32 v214, v72, v72
	v_add_f32_e32 v213, v213, v214
	v_add_f32_e32 v212, v212, v213
	v_mul_f32_e32 v213, v103, v103
	v_mul_f32_e32 v214, v105, v105
	v_fmac_f32_e32 v213, v102, v102
	v_fmac_f32_e32 v214, v104, v104
	v_add_f32_e32 v213, v213, v214
	v_add_f32_e32 v212, v212, v213
	v_mul_f32_e32 v213, v99, v99
	v_mul_f32_e32 v214, v101, v101
	v_fmac_f32_e32 v213, v98, v98
	v_fmac_f32_e32 v214, v100, v100
	v_add_f32_e32 v213, v213, v214
	v_add_f32_e32 v212, v212, v213
	v_mov_b32_e32 v213, v212
	s_nop 1
	v_permlane16_swap_b32_e32 v213, v212
	s_waitcnt lgkmcnt(0)
	v_add_f32_e32 v212, v212, v213
	v_mov_b32_e32 v213, v212
	s_nop 1
	v_permlane32_swap_b32_e32 v213, v212
	s_and_saveexec_b64 s[10:11], s[8:9]
	s_cbranch_execz .LBB0_409
	s_lshl_b32 s13, s57, 11
	s_add_i32 s13, s37, s13
	v_lshl_add_u32 v214, v219, 5, s13
	s_waitcnt lgkmcnt(0)
	v_add_f32_e32 v212, v212, v213
	v_mov_b32_e32 v213, v223
	ds_write_b64 v214, v[212:213] offset:1536
.LBB0_409:
	s_or_b64 exec, exec, s[10:11]
	v_mul_f32_e32 v212, v95, v95
	v_mul_f32_e32 v213, v97, v97
	v_fmac_f32_e32 v212, v94, v94
	v_fmac_f32_e32 v213, v96, v96
	v_add_f32_e32 v212, v212, v213
	v_mul_f32_e32 v213, v91, v91
	v_mul_f32_e32 v214, v93, v93
	v_fmac_f32_e32 v213, v90, v90
	v_fmac_f32_e32 v214, v92, v92
	v_add_f32_e32 v213, v213, v214
	v_add_f32_e32 v212, v212, v213
	v_mul_f32_e32 v213, v127, v127
	v_mul_f32_e32 v214, v129, v129
	v_fmac_f32_e32 v213, v126, v126
	v_fmac_f32_e32 v214, v128, v128
	v_add_f32_e32 v213, v213, v214
	v_add_f32_e32 v212, v212, v213
	v_mul_f32_e32 v213, v119, v119
	v_mul_f32_e32 v214, v121, v121
	v_fmac_f32_e32 v213, v118, v118
	v_fmac_f32_e32 v214, v120, v120
	v_add_f32_e32 v213, v213, v214
	v_add_f32_e32 v212, v212, v213
	v_mov_b32_e32 v213, v212
	s_nop 1
	v_permlane16_swap_b32_e32 v213, v212
	s_waitcnt lgkmcnt(0)
	v_add_f32_e32 v212, v212, v213
	v_mov_b32_e32 v213, v212
	s_nop 1
	v_permlane32_swap_b32_e32 v213, v212
	s_and_saveexec_b64 s[10:11], s[8:9]
	s_cbranch_execz .LBB0_411
	s_lshl_b32 s13, s57, 11
	s_add_i32 s13, s37, s13
	v_lshl_add_u32 v214, v219, 5, s13
	s_waitcnt lgkmcnt(0)
	v_add_f32_e32 v212, v212, v213
	v_mov_b32_e32 v213, v223
	ds_write_b64 v214, v[212:213] offset:4096
.LBB0_411:
	s_or_b64 exec, exec, s[10:11]
	v_mul_f32_e32 v212, v115, v115
	v_mul_f32_e32 v213, v117, v117
	v_fmac_f32_e32 v212, v114, v114
	v_fmac_f32_e32 v213, v116, v116
	v_add_f32_e32 v212, v212, v213
	v_mul_f32_e32 v213, v107, v107
	v_mul_f32_e32 v214, v109, v109
	v_fmac_f32_e32 v213, v106, v106
	v_fmac_f32_e32 v214, v108, v108
	v_add_f32_e32 v213, v213, v214
	v_add_f32_e32 v212, v212, v213
	v_mul_f32_e32 v213, v123, v123
	v_mul_f32_e32 v214, v125, v125
	v_fmac_f32_e32 v213, v122, v122
	v_fmac_f32_e32 v214, v124, v124
	v_add_f32_e32 v213, v213, v214
	v_add_f32_e32 v212, v212, v213
	v_mul_f32_e32 v213, v111, v111
	v_mul_f32_e32 v214, v113, v113
	v_fmac_f32_e32 v213, v110, v110
	v_fmac_f32_e32 v214, v112, v112
	v_add_f32_e32 v213, v213, v214
	v_add_f32_e32 v212, v212, v213
	v_mov_b32_e32 v213, v212
	s_nop 1
	v_permlane16_swap_b32_e32 v213, v212
	s_waitcnt lgkmcnt(0)
	v_add_f32_e32 v212, v212, v213
	v_mov_b32_e32 v213, v212
	s_nop 1
	v_permlane32_swap_b32_e32 v213, v212
	s_and_saveexec_b64 s[10:11], s[8:9]
	s_cbranch_execz .LBB0_413
	s_lshl_b32 s13, s57, 11
	s_add_i32 s13, s37, s13
	v_lshl_add_u32 v214, v219, 5, s13
	s_waitcnt lgkmcnt(0)
	v_add_f32_e32 v212, v212, v213
	v_mov_b32_e32 v213, v223
	ds_write_b64 v214, v[212:213] offset:4608
.LBB0_413:
	s_or_b64 exec, exec, s[10:11]
	v_mul_f32_e32 v212, v75, v75
	v_mul_f32_e32 v213, v77, v77
	v_fmac_f32_e32 v212, v74, v74
	v_fmac_f32_e32 v213, v76, v76
	v_add_f32_e32 v212, v212, v213
	v_mul_f32_e32 v213, v67, v67
	v_mul_f32_e32 v214, v69, v69
	v_fmac_f32_e32 v213, v66, v66
	v_fmac_f32_e32 v214, v68, v68
	v_add_f32_e32 v213, v213, v214
	v_add_f32_e32 v212, v212, v213
	v_mul_f32_e32 v213, v31, v31
	v_mul_f32_e32 v214, v33, v33
	v_fmac_f32_e32 v213, v30, v30
	v_fmac_f32_e32 v214, v32, v32
	v_add_f32_e32 v213, v213, v214
	v_add_f32_e32 v212, v212, v213
	v_mul_f32_e32 v213, v23, v23
	v_mul_f32_e32 v214, v25, v25
	v_fmac_f32_e32 v213, v22, v22
	v_fmac_f32_e32 v214, v24, v24
	v_add_f32_e32 v213, v213, v214
	v_add_f32_e32 v212, v212, v213
	v_mov_b32_e32 v213, v212
	s_nop 1
	v_permlane16_swap_b32_e32 v213, v212
	s_waitcnt lgkmcnt(0)
	v_add_f32_e32 v212, v212, v213
	v_mov_b32_e32 v213, v212
	s_nop 1
	v_permlane32_swap_b32_e32 v213, v212
	s_and_saveexec_b64 s[10:11], s[8:9]
	s_cbranch_execz .LBB0_415
	s_lshl_b32 s13, s57, 11
	s_add_i32 s13, s37, s13
	v_lshl_add_u32 v214, v219, 5, s13
	s_waitcnt lgkmcnt(0)
	v_add_f32_e32 v212, v212, v213
	v_mov_b32_e32 v213, v223
	ds_write_b64 v214, v[212:213] offset:5120
.LBB0_415:
	s_or_b64 exec, exec, s[10:11]
	v_mul_f32_e32 v212, v15, v15
	v_mul_f32_e32 v213, v17, v17
	v_fmac_f32_e32 v212, v14, v14
	v_fmac_f32_e32 v213, v16, v16
	v_add_f32_e32 v212, v212, v213
	v_mul_f32_e32 v213, v11, v11
	v_mul_f32_e32 v214, v13, v13
	v_fmac_f32_e32 v213, v10, v10
	v_fmac_f32_e32 v214, v12, v12
	v_add_f32_e32 v213, v213, v214
	v_add_f32_e32 v212, v212, v213
	v_mul_f32_e32 v213, v7, v7
	v_mul_f32_e32 v214, v9, v9
	v_fmac_f32_e32 v213, v6, v6
	v_fmac_f32_e32 v214, v8, v8
	v_add_f32_e32 v213, v213, v214
	v_add_f32_e32 v212, v212, v213
	v_mul_f32_e32 v213, v3, v3
	v_mul_f32_e32 v214, v5, v5
	v_fmac_f32_e32 v213, v2, v2
	v_fmac_f32_e32 v214, v4, v4
	v_add_f32_e32 v213, v213, v214
	v_add_f32_e32 v212, v212, v213
	v_mov_b32_e32 v213, v212
	s_nop 1
	v_permlane16_swap_b32_e32 v213, v212
	s_waitcnt lgkmcnt(0)
	v_add_f32_e32 v212, v212, v213
	v_mov_b32_e32 v213, v212
	s_nop 1
	v_permlane32_swap_b32_e32 v213, v212
	s_and_saveexec_b64 s[10:11], s[8:9]
	s_cbranch_execz .LBB0_417
	s_lshl_b32 s13, s57, 11
	s_add_i32 s13, s37, s13
	v_lshl_add_u32 v214, v219, 5, s13
	s_waitcnt lgkmcnt(0)
	v_add_f32_e32 v212, v212, v213
	v_mov_b32_e32 v213, v223
	ds_write_b64 v214, v[212:213] offset:5632

.LBB0_548:
	s_or_b64 exec, exec, s[6:7]
	v_pk_mul_f32 v[164:165], v[44:45], v[140:141]
	v_pk_mul_f32 v[166:167], v[42:43], v[138:139]
	v_max_f32_e64 v164, |v164|, |v165|
	v_max_f32_e64 v166, |v166|, |v167|
	v_max3_f32 v168, v166, 0, v164
	v_pk_mul_f32 v[164:165], v[36:37], v[148:149]
	v_pk_mul_f32 v[166:167], v[34:35], v[146:147]
	v_max_f32_e64 v164, |v164|, |v165|
	v_max_f32_e64 v166, |v166|, |v167|
	v_max3_f32 v168, v168, v166, v164
	v_pk_mul_f32 v[164:165], v[64:65], v[136:137]
	v_pk_mul_f32 v[166:167], v[62:63], v[134:135]
	v_max_f32_e64 v164, |v164|, |v165|
	v_max_f32_e64 v166, |v166|, |v167|
	v_max3_f32 v168, v168, v166, v164
	v_pk_mul_f32 v[164:165], v[60:61], v[132:133]
	v_pk_mul_f32 v[166:167], v[58:59], v[130:131]
	v_max_f32_e64 v164, |v164|, |v165|
	v_max_f32_e64 v166, |v166|, |v167|
	v_max3_f32 v166, v168, v166, v164
	v_mul_f32_e32 v164, v43, v43
	v_mul_f32_e32 v165, v45, v45
	v_fmac_f32_e32 v164, v42, v42
	v_fmac_f32_e32 v165, v44, v44
	v_add_f32_e32 v164, v164, v165
	v_mul_f32_e32 v165, v35, v35
	v_mul_f32_e32 v167, v37, v37
	v_fmac_f32_e32 v165, v34, v34
	v_fmac_f32_e32 v167, v36, v36
	v_add_f32_e32 v165, v165, v167
	v_add_f32_e32 v164, v164, v165
	v_mul_f32_e32 v165, v63, v63
	v_mul_f32_e32 v167, v65, v65
	v_fmac_f32_e32 v165, v62, v62
	v_fmac_f32_e32 v167, v64, v64
	v_add_f32_e32 v165, v165, v167
	v_add_f32_e32 v164, v165, v164
	v_mul_f32_e32 v165, v59, v59
	v_mul_f32_e32 v167, v61, v61
	v_fmac_f32_e32 v165, v58, v58
	v_fmac_f32_e32 v167, v60, v60
	v_add_f32_e32 v165, v165, v167
	v_add_f32_e32 v164, v165, v164
	v_mov_b32_e32 v167, v166
	v_mov_b32_e32 v165, v164
	s_nop 1
	v_permlane16_swap_b32_e32 v167, v166
	v_permlane16_swap_b32_e32 v165, v164
	s_waitcnt lgkmcnt(1)
	v_max_f32_e32 v167, v167, v167
	s_waitcnt lgkmcnt(0)
	v_add_f32_e32 v164, v164, v165
	v_max_f32_e32 v166, v166, v167
	v_mov_b32_e32 v165, v164
	v_mov_b32_e32 v167, v166
	s_nop 1
	v_permlane32_swap_b32_e32 v165, v164
	v_permlane32_swap_b32_e32 v167, v166
	s_and_saveexec_b64 s[6:7], s[8:9]
	s_cbranch_execz .LBB0_550
	s_lshl_b32 s18, s57, 11
	s_add_i32 s18, s37, s18
	s_waitcnt lgkmcnt(1)
	v_add_f32_e32 v164, v164, v165
	s_waitcnt lgkmcnt(0)
	v_max_f32_e32 v165, v167, v167
	v_max_f32_e32 v166, v166, v166
	v_lshl_add_u32 v168, v219, 5, s18
	v_max_f32_e32 v165, v166, v165
	ds_write_b64 v168, v[164:165] offset:512
.LBB0_550:
	s_or_b64 exec, exec, s[6:7]
	v_pk_mul_f32 v[164:165], v[56:57], v[140:141]
	v_pk_mul_f32 v[166:167], v[54:55], v[138:139]
	v_max_f32_e64 v164, |v164|, |v165|
	v_max_f32_e64 v166, |v166|, |v167|
	v_max3_f32 v168, v166, 0, v164
	v_pk_mul_f32 v[164:165], v[52:53], v[148:149]
	v_pk_mul_f32 v[166:167], v[50:51], v[146:147]
	v_max_f32_e64 v164, |v164|, |v165|
	v_max_f32_e64 v166, |v166|, |v167|
	v_max3_f32 v168, v168, v166, v164
	v_pk_mul_f32 v[164:165], v[88:89], v[136:137]
	v_pk_mul_f32 v[166:167], v[86:87], v[134:135]
	v_max_f32_e64 v164, |v164|, |v165|
	v_max_f32_e64 v166, |v166|, |v167|
	v_max3_f32 v168, v168, v166, v164
	v_pk_mul_f32 v[164:165], v[84:85], v[132:133]
	v_pk_mul_f32 v[166:167], v[82:83], v[130:131]
	v_max_f32_e64 v164, |v164|, |v165|
	v_max_f32_e64 v166, |v166|, |v167|
	v_max3_f32 v166, v168, v166, v164
	v_mul_f32_e32 v164, v55, v55
	v_mul_f32_e32 v165, v57, v57
	v_fmac_f32_e32 v164, v54, v54
	v_fmac_f32_e32 v165, v56, v56
	v_add_f32_e32 v164, v164, v165
	v_mul_f32_e32 v165, v51, v51
	v_mul_f32_e32 v167, v53, v53
	v_fmac_f32_e32 v165, v50, v50
	v_fmac_f32_e32 v167, v52, v52
	v_add_f32_e32 v165, v165, v167
	v_add_f32_e32 v164, v164, v165
	v_mul_f32_e32 v165, v87, v87
	v_mul_f32_e32 v167, v89, v89
	v_fmac_f32_e32 v165, v86, v86
	v_fmac_f32_e32 v167, v88, v88
	v_add_f32_e32 v165, v165, v167
	v_add_f32_e32 v164, v165, v164
	v_mul_f32_e32 v165, v83, v83
	v_mul_f32_e32 v167, v85, v85
	v_fmac_f32_e32 v165, v82, v82
	v_fmac_f32_e32 v167, v84, v84
	v_add_f32_e32 v165, v165, v167
	v_add_f32_e32 v164, v165, v164
	v_mov_b32_e32 v167, v166
	v_mov_b32_e32 v165, v164
	s_nop 1
	v_permlane16_swap_b32_e32 v167, v166
	v_permlane16_swap_b32_e32 v165, v164
	s_waitcnt lgkmcnt(1)
	v_max_f32_e32 v167, v167, v167
	s_waitcnt lgkmcnt(0)
	v_add_f32_e32 v164, v164, v165
	v_max_f32_e32 v166, v166, v167
	v_mov_b32_e32 v165, v164
	v_mov_b32_e32 v167, v166
	s_nop 1
	v_permlane32_swap_b32_e32 v165, v164
	v_permlane32_swap_b32_e32 v167, v166
	s_and_saveexec_b64 s[6:7], s[8:9]
	s_cbranch_execz .LBB0_552
	s_lshl_b32 s18, s57, 11
	s_add_i32 s18, s37, s18
	s_waitcnt lgkmcnt(1)
	v_add_f32_e32 v164, v164, v165
	s_waitcnt lgkmcnt(0)
	v_max_f32_e32 v165, v167, v167
	v_max_f32_e32 v166, v166, v166
	v_lshl_add_u32 v168, v219, 5, s18
	v_max_f32_e32 v165, v166, v165
	ds_write_b64 v168, v[164:165] offset:1024
.LBB0_552:
	s_or_b64 exec, exec, s[6:7]
	v_pk_mul_f32 v[164:165], v[80:81], v[140:141]
	v_pk_mul_f32 v[166:167], v[78:79], v[138:139]
	v_max_f32_e64 v164, |v164|, |v165|
	v_max_f32_e64 v166, |v166|, |v167|
	v_max3_f32 v168, v166, 0, v164
	v_pk_mul_f32 v[164:165], v[72:73], v[148:149]
	v_pk_mul_f32 v[166:167], v[70:71], v[146:147]
	v_max_f32_e64 v164, |v164|, |v165|
	v_max_f32_e64 v166, |v166|, |v167|
	v_max3_f32 v168, v168, v166, v164
	v_pk_mul_f32 v[164:165], v[104:105], v[136:137]
	v_pk_mul_f32 v[166:167], v[102:103], v[134:135]
	v_max_f32_e64 v164, |v164|, |v165|
	v_max_f32_e64 v166, |v166|, |v167|
	v_max3_f32 v168, v168, v166, v164
	v_pk_mul_f32 v[164:165], v[100:101], v[132:133]
	v_pk_mul_f32 v[166:167], v[98:99], v[130:131]
	v_max_f32_e64 v164, |v164|, |v165|
	v_max_f32_e64 v166, |v166|, |v167|
	v_max3_f32 v166, v168, v166, v164
	v_mul_f32_e32 v164, v79, v79
	v_mul_f32_e32 v165, v81, v81
	v_fmac_f32_e32 v164, v78, v78
	v_fmac_f32_e32 v165, v80, v80
	v_add_f32_e32 v164, v164, v165
	v_mul_f32_e32 v165, v71, v71
	v_mul_f32_e32 v167, v73, v73
	v_fmac_f32_e32 v165, v70, v70
	v_fmac_f32_e32 v167, v72, v72
	v_add_f32_e32 v165, v165, v167
	v_add_f32_e32 v164, v164, v165
	v_mul_f32_e32 v165, v103, v103
	v_mul_f32_e32 v167, v105, v105
	v_fmac_f32_e32 v165, v102, v102
	v_fmac_f32_e32 v167, v104, v104
	v_add_f32_e32 v165, v165, v167
	v_add_f32_e32 v164, v165, v164
	v_mul_f32_e32 v165, v99, v99
	v_mul_f32_e32 v167, v101, v101
	v_fmac_f32_e32 v165, v98, v98
	v_fmac_f32_e32 v167, v100, v100
	v_add_f32_e32 v165, v165, v167
	v_add_f32_e32 v164, v165, v164
	v_mov_b32_e32 v167, v166
	v_mov_b32_e32 v165, v164
	s_nop 1
	v_permlane16_swap_b32_e32 v167, v166
	v_permlane16_swap_b32_e32 v165, v164
	s_waitcnt lgkmcnt(1)
	v_max_f32_e32 v167, v167, v167
	s_waitcnt lgkmcnt(0)
	v_add_f32_e32 v164, v164, v165
	v_max_f32_e32 v166, v166, v167
	v_mov_b32_e32 v165, v164
	v_mov_b32_e32 v167, v166
	s_nop 1
	v_permlane32_swap_b32_e32 v165, v164
	v_permlane32_swap_b32_e32 v167, v166
	s_and_saveexec_b64 s[6:7], s[8:9]
	s_cbranch_execz .LBB0_554
	s_lshl_b32 s18, s57, 11
	s_add_i32 s18, s37, s18
	s_waitcnt lgkmcnt(1)
	v_add_f32_e32 v164, v164, v165
	s_waitcnt lgkmcnt(0)
	v_max_f32_e32 v165, v167, v167
	v_max_f32_e32 v166, v166, v166
	v_lshl_add_u32 v168, v219, 5, s18
	v_max_f32_e32 v165, v166, v165
	ds_write_b64 v168, v[164:165] offset:1536
.LBB0_554:
	s_or_b64 exec, exec, s[6:7]
	v_pk_mul_f32 v[164:165], v[96:97], v[140:141]
	v_pk_mul_f32 v[166:167], v[94:95], v[138:139]
	v_max_f32_e64 v164, |v164|, |v165|
	v_max_f32_e64 v166, |v166|, |v167|
	v_max3_f32 v168, v166, 0, v164
	v_pk_mul_f32 v[164:165], v[92:93], v[148:149]
	v_pk_mul_f32 v[166:167], v[90:91], v[146:147]
	v_max_f32_e64 v164, |v164|, |v165|
	v_max_f32_e64 v166, |v166|, |v167|
	v_max3_f32 v168, v168, v166, v164
	v_pk_mul_f32 v[164:165], v[128:129], v[136:137]
	v_pk_mul_f32 v[166:167], v[126:127], v[134:135]
	v_max_f32_e64 v164, |v164|, |v165|
	v_max_f32_e64 v166, |v166|, |v167|
	v_max3_f32 v168, v168, v166, v164
	v_pk_mul_f32 v[164:165], v[120:121], v[132:133]
	v_pk_mul_f32 v[166:167], v[118:119], v[130:131]
	v_max_f32_e64 v164, |v164|, |v165|
	v_max_f32_e64 v166, |v166|, |v167|
	v_max3_f32 v166, v168, v166, v164
	v_mul_f32_e32 v164, v95, v95
	v_mul_f32_e32 v165, v97, v97
	v_fmac_f32_e32 v164, v94, v94
	v_fmac_f32_e32 v165, v96, v96
	v_add_f32_e32 v164, v164, v165
	v_mul_f32_e32 v165, v91, v91
	v_mul_f32_e32 v167, v93, v93
	v_fmac_f32_e32 v165, v90, v90
	v_fmac_f32_e32 v167, v92, v92
	v_add_f32_e32 v165, v165, v167
	v_add_f32_e32 v164, v164, v165
	v_mul_f32_e32 v165, v127, v127
	v_mul_f32_e32 v167, v129, v129
	v_fmac_f32_e32 v165, v126, v126
	v_fmac_f32_e32 v167, v128, v128
	v_add_f32_e32 v165, v165, v167
	v_add_f32_e32 v164, v165, v164
	v_mul_f32_e32 v165, v119, v119
	v_mul_f32_e32 v167, v121, v121
	v_fmac_f32_e32 v165, v118, v118
	v_fmac_f32_e32 v167, v120, v120
	v_add_f32_e32 v165, v165, v167
	v_add_f32_e32 v164, v165, v164
	v_mov_b32_e32 v167, v166
	v_mov_b32_e32 v165, v164
	s_nop 1
	v_permlane16_swap_b32_e32 v167, v166
	v_permlane16_swap_b32_e32 v165, v164
	s_waitcnt lgkmcnt(1)
	v_max_f32_e32 v167, v167, v167
	s_waitcnt lgkmcnt(0)
	v_add_f32_e32 v164, v164, v165
	v_max_f32_e32 v166, v166, v167
	v_mov_b32_e32 v165, v164
	v_mov_b32_e32 v167, v166
	s_nop 1
	v_permlane32_swap_b32_e32 v165, v164
	v_permlane32_swap_b32_e32 v167, v166
	s_and_saveexec_b64 s[6:7], s[8:9]
	s_cbranch_execz .LBB0_556
	s_lshl_b32 s18, s57, 11
	s_add_i32 s18, s37, s18
	s_waitcnt lgkmcnt(1)
	v_add_f32_e32 v164, v164, v165
	s_waitcnt lgkmcnt(0)
	v_max_f32_e32 v165, v167, v167
	v_max_f32_e32 v166, v166, v166
	v_lshl_add_u32 v168, v219, 5, s18
	v_max_f32_e32 v165, v166, v165
	ds_write_b64 v168, v[164:165] offset:4096
.LBB0_556:
	s_or_b64 exec, exec, s[6:7]
	v_pk_mul_f32 v[164:165], v[116:117], v[140:141]
	v_pk_mul_f32 v[166:167], v[114:115], v[138:139]
	v_max_f32_e64 v164, |v164|, |v165|
	v_max_f32_e64 v166, |v166|, |v167|
	v_max3_f32 v168, v166, 0, v164
	v_pk_mul_f32 v[164:165], v[108:109], v[148:149]
	v_pk_mul_f32 v[166:167], v[106:107], v[146:147]
	v_max_f32_e64 v164, |v164|, |v165|
	v_max_f32_e64 v166, |v166|, |v167|
	v_max3_f32 v168, v168, v166, v164
	v_pk_mul_f32 v[164:165], v[124:125], v[136:137]
	v_pk_mul_f32 v[166:167], v[122:123], v[134:135]
	v_max_f32_e64 v164, |v164|, |v165|
	v_max_f32_e64 v166, |v166|, |v167|
	v_max3_f32 v168, v168, v166, v164
	v_pk_mul_f32 v[164:165], v[112:113], v[132:133]
	v_pk_mul_f32 v[166:167], v[110:111], v[130:131]
	v_max_f32_e64 v164, |v164|, |v165|
	v_max_f32_e64 v166, |v166|, |v167|
	v_max3_f32 v166, v168, v166, v164
	v_mul_f32_e32 v164, v115, v115
	v_mul_f32_e32 v165, v117, v117
	v_fmac_f32_e32 v164, v114, v114
	v_fmac_f32_e32 v165, v116, v116
	v_add_f32_e32 v164, v164, v165
	v_mul_f32_e32 v165, v107, v107
	v_mul_f32_e32 v167, v109, v109
	v_fmac_f32_e32 v165, v106, v106
	v_fmac_f32_e32 v167, v108, v108
	v_add_f32_e32 v165, v165, v167
	v_add_f32_e32 v164, v164, v165
	v_mul_f32_e32 v165, v123, v123
	v_mul_f32_e32 v167, v125, v125
	v_fmac_f32_e32 v165, v122, v122
	v_fmac_f32_e32 v167, v124, v124
	v_add_f32_e32 v165, v165, v167
	v_add_f32_e32 v164, v165, v164
	v_mul_f32_e32 v165, v111, v111
	v_mul_f32_e32 v167, v113, v113
	v_fmac_f32_e32 v165, v110, v110
	v_fmac_f32_e32 v167, v112, v112
	v_add_f32_e32 v165, v165, v167
	v_add_f32_e32 v164, v165, v164
	v_mov_b32_e32 v167, v166
	v_mov_b32_e32 v165, v164
	s_nop 1
	v_permlane16_swap_b32_e32 v167, v166
	v_permlane16_swap_b32_e32 v165, v164
	s_waitcnt lgkmcnt(1)
	v_max_f32_e32 v167, v167, v167
	s_waitcnt lgkmcnt(0)
	v_add_f32_e32 v164, v164, v165
	v_max_f32_e32 v166, v166, v167
	v_mov_b32_e32 v165, v164
	v_mov_b32_e32 v167, v166
	s_nop 1
	v_permlane32_swap_b32_e32 v165, v164
	v_permlane32_swap_b32_e32 v167, v166
	s_and_saveexec_b64 s[6:7], s[8:9]
	s_cbranch_execz .LBB0_558
	s_lshl_b32 s18, s57, 11
	s_add_i32 s18, s37, s18
	s_waitcnt lgkmcnt(1)
	v_add_f32_e32 v164, v164, v165
	s_waitcnt lgkmcnt(0)
	v_max_f32_e32 v165, v167, v167
	v_max_f32_e32 v166, v166, v166
	v_lshl_add_u32 v168, v219, 5, s18
	v_max_f32_e32 v165, v166, v165
	ds_write_b64 v168, v[164:165] offset:4608
.LBB0_558:
	s_or_b64 exec, exec, s[6:7]
	v_pk_mul_f32 v[164:165], v[76:77], v[140:141]
	v_pk_mul_f32 v[166:167], v[74:75], v[138:139]
	v_max_f32_e64 v164, |v164|, |v165|
	v_max_f32_e64 v166, |v166|, |v167|
	v_max3_f32 v168, v166, 0, v164
	v_pk_mul_f32 v[164:165], v[68:69], v[148:149]
	v_pk_mul_f32 v[166:167], v[66:67], v[146:147]
	v_max_f32_e64 v164, |v164|, |v165|
	v_max_f32_e64 v166, |v166|, |v167|
	v_max3_f32 v168, v168, v166, v164
	v_pk_mul_f32 v[164:165], v[32:33], v[136:137]
	v_pk_mul_f32 v[166:167], v[30:31], v[134:135]
	v_max_f32_e64 v164, |v164|, |v165|
	v_max_f32_e64 v166, |v166|, |v167|
	v_max3_f32 v168, v168, v166, v164
	v_pk_mul_f32 v[164:165], v[24:25], v[132:133]
	v_pk_mul_f32 v[166:167], v[22:23], v[130:131]
	v_max_f32_e64 v164, |v164|, |v165|
	v_max_f32_e64 v166, |v166|, |v167|
	v_max3_f32 v166, v168, v166, v164
	v_mul_f32_e32 v164, v75, v75
	v_mul_f32_e32 v165, v77, v77
	v_fmac_f32_e32 v164, v74, v74
	v_fmac_f32_e32 v165, v76, v76
	v_add_f32_e32 v164, v164, v165
	v_mul_f32_e32 v165, v67, v67
	v_mul_f32_e32 v167, v69, v69
	v_fmac_f32_e32 v165, v66, v66
	v_fmac_f32_e32 v167, v68, v68
	v_add_f32_e32 v165, v165, v167
	v_add_f32_e32 v164, v164, v165
	v_mul_f32_e32 v165, v31, v31
	v_mul_f32_e32 v167, v33, v33
	v_fmac_f32_e32 v165, v30, v30
	v_fmac_f32_e32 v167, v32, v32
	v_add_f32_e32 v165, v165, v167
	v_add_f32_e32 v164, v165, v164
	v_mul_f32_e32 v165, v23, v23
	v_mul_f32_e32 v167, v25, v25
	v_fmac_f32_e32 v165, v22, v22
	v_fmac_f32_e32 v167, v24, v24
	v_add_f32_e32 v165, v165, v167
	v_add_f32_e32 v164, v165, v164
	v_mov_b32_e32 v167, v166
	v_mov_b32_e32 v165, v164
	s_nop 1
	v_permlane16_swap_b32_e32 v167, v166
	v_permlane16_swap_b32_e32 v165, v164
	s_waitcnt lgkmcnt(1)
	v_max_f32_e32 v167, v167, v167
	s_waitcnt lgkmcnt(0)
	v_add_f32_e32 v164, v164, v165
	v_max_f32_e32 v166, v166, v167
	v_mov_b32_e32 v165, v164
	v_mov_b32_e32 v167, v166
	s_nop 1
	v_permlane32_swap_b32_e32 v165, v164
	v_permlane32_swap_b32_e32 v167, v166
	s_and_saveexec_b64 s[6:7], s[8:9]
	s_cbranch_execz .LBB0_560
	s_lshl_b32 s18, s57, 11
	s_add_i32 s18, s37, s18
	s_waitcnt lgkmcnt(1)
	v_add_f32_e32 v164, v164, v165
	s_waitcnt lgkmcnt(0)
	v_max_f32_e32 v165, v167, v167
	v_max_f32_e32 v166, v166, v166
	v_lshl_add_u32 v168, v219, 5, s18
	v_max_f32_e32 v165, v166, v165
	ds_write_b64 v168, v[164:165] offset:5120
.LBB0_560:
	s_or_b64 exec, exec, s[6:7]
	v_pk_mul_f32 v[164:165], v[16:17], v[140:141]
	v_pk_mul_f32 v[166:167], v[14:15], v[138:139]
	v_max_f32_e64 v164, |v164|, |v165|
	v_max_f32_e64 v166, |v166|, |v167|
	v_max3_f32 v168, v166, 0, v164
	v_pk_mul_f32 v[164:165], v[12:13], v[148:149]
	v_pk_mul_f32 v[166:167], v[10:11], v[146:147]
	v_max_f32_e64 v164, |v164|, |v165|
	v_max_f32_e64 v166, |v166|, |v167|
	v_max3_f32 v168, v168, v166, v164
	v_pk_mul_f32 v[164:165], v[8:9], v[136:137]
	v_pk_mul_f32 v[166:167], v[6:7], v[134:135]
	v_max_f32_e64 v164, |v164|, |v165|
	v_max_f32_e64 v166, |v166|, |v167|
	v_max3_f32 v168, v168, v166, v164
	v_pk_mul_f32 v[164:165], v[4:5], v[132:133]
	v_pk_mul_f32 v[166:167], v[2:3], v[130:131]
	v_max_f32_e64 v164, |v164|, |v165|
	v_max_f32_e64 v166, |v166|, |v167|
	v_max3_f32 v166, v168, v166, v164
	v_mul_f32_e32 v164, v15, v15
	v_mul_f32_e32 v165, v17, v17
	v_fmac_f32_e32 v164, v14, v14
	v_fmac_f32_e32 v165, v16, v16
	v_add_f32_e32 v164, v164, v165
	v_mul_f32_e32 v165, v11, v11
	v_mul_f32_e32 v167, v13, v13
	v_fmac_f32_e32 v165, v10, v10
	v_fmac_f32_e32 v167, v12, v12
	v_add_f32_e32 v165, v165, v167
	v_add_f32_e32 v164, v164, v165
	v_mul_f32_e32 v165, v7, v7
	v_mul_f32_e32 v167, v9, v9
	v_fmac_f32_e32 v165, v6, v6
	v_fmac_f32_e32 v167, v8, v8
	v_add_f32_e32 v165, v165, v167
	v_add_f32_e32 v164, v165, v164
	v_mul_f32_e32 v165, v3, v3
	v_mul_f32_e32 v167, v5, v5
	v_fmac_f32_e32 v165, v2, v2
	v_fmac_f32_e32 v167, v4, v4
	v_add_f32_e32 v165, v165, v167
	v_add_f32_e32 v164, v165, v164
	v_mov_b32_e32 v167, v166
	v_mov_b32_e32 v165, v164
	s_nop 1
	v_permlane16_swap_b32_e32 v167, v166
	v_permlane16_swap_b32_e32 v165, v164
	s_waitcnt lgkmcnt(1)
	v_max_f32_e32 v167, v167, v167
	s_waitcnt lgkmcnt(0)
	v_add_f32_e32 v164, v164, v165
	v_max_f32_e32 v166, v166, v167
	v_mov_b32_e32 v165, v164
	v_mov_b32_e32 v167, v166
	s_nop 1
	v_permlane32_swap_b32_e32 v165, v164
	v_permlane32_swap_b32_e32 v167, v166
	s_and_saveexec_b64 s[6:7], s[8:9]
	s_cbranch_execz .LBB0_562
	s_lshl_b32 s8, s57, 11
	s_add_i32 s37, s37, s8
	s_waitcnt lgkmcnt(1)
	v_add_f32_e32 v164, v164, v165
	s_waitcnt lgkmcnt(0)
	v_max_f32_e32 v165, v167, v167
	v_max_f32_e32 v166, v166, v166
	v_lshl_add_u32 v168, v219, 5, s37
	v_max_f32_e32 v165, v166, v165
	ds_write_b64 v168, v[164:165] offset:5632

.LBB0_1198:
	s_or_b64 exec, exec, s[8:9]
	v_mul_f32_e32 v212, v55, v55
	v_mul_f32_e32 v213, v57, v57
	v_fmac_f32_e32 v212, v54, v54
	v_fmac_f32_e32 v213, v56, v56
	v_add_f32_e32 v212, v212, v213
	v_mul_f32_e32 v213, v51, v51
	v_mul_f32_e32 v214, v53, v53
	v_fmac_f32_e32 v213, v50, v50
	v_fmac_f32_e32 v214, v52, v52
	v_add_f32_e32 v213, v213, v214
	v_add_f32_e32 v212, v212, v213
	v_mul_f32_e32 v213, v67, v67
	v_mul_f32_e32 v214, v69, v69
	v_fmac_f32_e32 v213, v66, v66
	v_fmac_f32_e32 v214, v68, v68
	v_add_f32_e32 v213, v213, v214
	v_add_f32_e32 v212, v212, v213
	v_mul_f32_e32 v213, v59, v59
	v_mul_f32_e32 v214, v61, v61
	v_fmac_f32_e32 v213, v58, v58
	v_fmac_f32_e32 v214, v60, v60
	v_add_f32_e32 v213, v213, v214
	v_add_f32_e32 v212, v212, v213
	v_mov_b32_e32 v213, v212
	s_nop 1
	v_permlane16_swap_b32_e32 v213, v212
	s_waitcnt lgkmcnt(0)
	v_add_f32_e32 v212, v212, v213
	v_mov_b32_e32 v213, v212
	s_nop 1
	v_permlane32_swap_b32_e32 v213, v212
	s_and_saveexec_b64 s[8:9], s[6:7]
	s_cbranch_execz .LBB0_1200
	s_lshl_b32 s11, s83, 11
	s_add_i32 s11, s45, s11
	v_lshl_add_u32 v214, v219, 5, s11
	s_waitcnt lgkmcnt(0)
	v_add_f32_e32 v212, v212, v213
	v_mov_b32_e32 v213, v223
	ds_write_b64 v214, v[212:213] offset:512
.LBB0_1200:
	s_or_b64 exec, exec, s[8:9]
	v_mul_f32_e32 v212, v79, v79
	v_mul_f32_e32 v213, v81, v81
	v_fmac_f32_e32 v212, v78, v78
	v_fmac_f32_e32 v213, v80, v80
	v_add_f32_e32 v212, v212, v213
	v_mul_f32_e32 v213, v75, v75
	v_mul_f32_e32 v214, v77, v77
	v_fmac_f32_e32 v213, v74, v74
	v_fmac_f32_e32 v214, v76, v76
	v_add_f32_e32 v213, v213, v214
	v_add_f32_e32 v212, v212, v213
	v_mul_f32_e32 v213, v87, v87
	v_mul_f32_e32 v214, v89, v89
	v_fmac_f32_e32 v213, v86, v86
	v_fmac_f32_e32 v214, v88, v88
	v_add_f32_e32 v213, v213, v214
	v_add_f32_e32 v212, v212, v213
	v_mul_f32_e32 v213, v83, v83
	v_mul_f32_e32 v214, v85, v85
	v_fmac_f32_e32 v213, v82, v82
	v_fmac_f32_e32 v214, v84, v84
	v_add_f32_e32 v213, v213, v214
	v_add_f32_e32 v212, v212, v213
	v_mov_b32_e32 v213, v212
	s_nop 1
	v_permlane16_swap_b32_e32 v213, v212
	s_waitcnt lgkmcnt(0)
	v_add_f32_e32 v212, v212, v213
	v_mov_b32_e32 v213, v212
	s_nop 1
	v_permlane32_swap_b32_e32 v213, v212
	s_and_saveexec_b64 s[8:9], s[6:7]
	s_cbranch_execz .LBB0_1202
	s_lshl_b32 s11, s83, 11
	s_add_i32 s11, s45, s11
	v_lshl_add_u32 v214, v219, 5, s11
	s_waitcnt lgkmcnt(0)
	v_add_f32_e32 v212, v212, v213
	v_mov_b32_e32 v213, v223
	ds_write_b64 v214, v[212:213] offset:1024
.LBB0_1202:
	s_or_b64 exec, exec, s[8:9]
	v_mul_f32_e32 v212, v103, v103
	v_mul_f32_e32 v213, v105, v105
	v_fmac_f32_e32 v212, v102, v102
	v_fmac_f32_e32 v213, v104, v104
	v_add_f32_e32 v212, v212, v213
	v_mul_f32_e32 v213, v95, v95
	v_mul_f32_e32 v214, v97, v97
	v_fmac_f32_e32 v213, v94, v94
	v_fmac_f32_e32 v214, v96, v96
	v_add_f32_e32 v213, v213, v214
	v_add_f32_e32 v212, v212, v213
	v_mul_f32_e32 v213, v111, v111
	v_mul_f32_e32 v214, v113, v113
	v_fmac_f32_e32 v213, v110, v110
	v_fmac_f32_e32 v214, v112, v112
	v_add_f32_e32 v213, v213, v214
	v_add_f32_e32 v212, v212, v213
	v_mul_f32_e32 v213, v107, v107
	v_mul_f32_e32 v214, v109, v109
	v_fmac_f32_e32 v213, v106, v106
	v_fmac_f32_e32 v214, v108, v108
	v_add_f32_e32 v213, v213, v214
	v_add_f32_e32 v212, v212, v213
	v_mov_b32_e32 v213, v212
	s_nop 1
	v_permlane16_swap_b32_e32 v213, v212
	s_waitcnt lgkmcnt(0)
	v_add_f32_e32 v212, v212, v213
	v_mov_b32_e32 v213, v212
	s_nop 1
	v_permlane32_swap_b32_e32 v213, v212
	s_and_saveexec_b64 s[8:9], s[6:7]
	s_cbranch_execz .LBB0_1204
	s_lshl_b32 s11, s83, 11
	s_add_i32 s11, s45, s11
	v_lshl_add_u32 v214, v219, 5, s11
	s_waitcnt lgkmcnt(0)
	v_add_f32_e32 v212, v212, v213
	v_mov_b32_e32 v213, v223
	ds_write_b64 v214, v[212:213] offset:1536
.LBB0_1204:
	s_or_b64 exec, exec, s[8:9]
	v_mul_f32_e32 v212, v127, v127
	v_mul_f32_e32 v213, v129, v129
	v_fmac_f32_e32 v212, v126, v126
	v_fmac_f32_e32 v213, v128, v128
	v_add_f32_e32 v212, v212, v213
	v_mul_f32_e32 v213, v119, v119
	v_mul_f32_e32 v214, v121, v121
	v_fmac_f32_e32 v213, v118, v118
	v_fmac_f32_e32 v214, v120, v120
	v_add_f32_e32 v213, v213, v214
	v_add_f32_e32 v212, v212, v213
	v_mul_f32_e32 v213, v123, v123
	v_mul_f32_e32 v214, v125, v125
	v_fmac_f32_e32 v213, v122, v122
	v_fmac_f32_e32 v214, v124, v124
	v_add_f32_e32 v213, v213, v214
	v_add_f32_e32 v212, v212, v213
	v_mul_f32_e32 v213, v115, v115
	v_mul_f32_e32 v214, v117, v117
	v_fmac_f32_e32 v213, v114, v114
	v_fmac_f32_e32 v214, v116, v116
	v_add_f32_e32 v213, v213, v214
	v_add_f32_e32 v212, v212, v213
	v_mov_b32_e32 v213, v212
	s_nop 1
	v_permlane16_swap_b32_e32 v213, v212
	s_waitcnt lgkmcnt(0)
	v_add_f32_e32 v212, v212, v213
	v_mov_b32_e32 v213, v212
	s_nop 1
	v_permlane32_swap_b32_e32 v213, v212
	s_and_saveexec_b64 s[8:9], s[6:7]
	s_cbranch_execz .LBB0_1206
	s_lshl_b32 s11, s83, 11
	s_add_i32 s11, s45, s11
	v_lshl_add_u32 v214, v219, 5, s11
	s_waitcnt lgkmcnt(0)
	v_add_f32_e32 v212, v212, v213
	v_mov_b32_e32 v213, v223
	ds_write_b64 v214, v[212:213] offset:4096
.LBB0_1206:
	s_or_b64 exec, exec, s[8:9]
	v_mul_f32_e32 v212, v99, v99
	v_mul_f32_e32 v213, v101, v101
	v_fmac_f32_e32 v212, v98, v98
	v_fmac_f32_e32 v213, v100, v100
	v_add_f32_e32 v212, v212, v213
	v_mul_f32_e32 v213, v91, v91
	v_mul_f32_e32 v214, v93, v93
	v_fmac_f32_e32 v213, v90, v90
	v_fmac_f32_e32 v214, v92, v92
	v_add_f32_e32 v213, v213, v214
	v_add_f32_e32 v212, v212, v213
	v_mul_f32_e32 v213, v71, v71
	v_mul_f32_e32 v214, v73, v73
	v_fmac_f32_e32 v213, v70, v70
	v_fmac_f32_e32 v214, v72, v72
	v_add_f32_e32 v213, v213, v214
	v_add_f32_e32 v212, v212, v213
	v_mul_f32_e32 v213, v63, v63
	v_mul_f32_e32 v214, v65, v65
	v_fmac_f32_e32 v213, v62, v62
	v_fmac_f32_e32 v214, v64, v64
	v_add_f32_e32 v213, v213, v214
	v_add_f32_e32 v212, v212, v213
	v_mov_b32_e32 v213, v212
	s_nop 1
	v_permlane16_swap_b32_e32 v213, v212
	s_waitcnt lgkmcnt(0)
	v_add_f32_e32 v212, v212, v213
	v_mov_b32_e32 v213, v212
	s_nop 1
	v_permlane32_swap_b32_e32 v213, v212
	s_and_saveexec_b64 s[8:9], s[6:7]
	s_cbranch_execz .LBB0_1208
	s_lshl_b32 s11, s83, 11
	s_add_i32 s11, s45, s11
	v_lshl_add_u32 v214, v219, 5, s11
	s_waitcnt lgkmcnt(0)
	v_add_f32_e32 v212, v212, v213
	v_mov_b32_e32 v213, v223
	ds_write_b64 v214, v[212:213] offset:4608
.LBB0_1208:
	s_or_b64 exec, exec, s[8:9]
	v_mul_f32_e32 v212, v47, v47
	v_mul_f32_e32 v213, v49, v49
	v_fmac_f32_e32 v212, v46, v46
	v_fmac_f32_e32 v213, v48, v48
	v_add_f32_e32 v212, v212, v213
	v_mul_f32_e32 v213, v39, v39
	v_mul_f32_e32 v214, v41, v41
	v_fmac_f32_e32 v213, v38, v38
	v_fmac_f32_e32 v214, v40, v40
	v_add_f32_e32 v213, v213, v214
	v_add_f32_e32 v212, v212, v213
	v_mul_f32_e32 v213, v23, v23
	v_mul_f32_e32 v214, v25, v25
	v_fmac_f32_e32 v213, v22, v22
	v_fmac_f32_e32 v214, v24, v24
	v_add_f32_e32 v213, v213, v214
	v_add_f32_e32 v212, v212, v213
	v_mul_f32_e32 v213, v19, v19
	v_mul_f32_e32 v214, v21, v21
	v_fmac_f32_e32 v213, v18, v18
	v_fmac_f32_e32 v214, v20, v20
	v_add_f32_e32 v213, v213, v214
	v_add_f32_e32 v212, v212, v213
	v_mov_b32_e32 v213, v212
	s_nop 1
	v_permlane16_swap_b32_e32 v213, v212
	s_waitcnt lgkmcnt(0)
	v_add_f32_e32 v212, v212, v213
	v_mov_b32_e32 v213, v212
	s_nop 1
	v_permlane32_swap_b32_e32 v213, v212
	s_and_saveexec_b64 s[8:9], s[6:7]
	s_cbranch_execz .LBB0_1210
	s_lshl_b32 s11, s83, 11
	s_add_i32 s11, s45, s11
	v_lshl_add_u32 v214, v219, 5, s11
	s_waitcnt lgkmcnt(0)
	v_add_f32_e32 v212, v212, v213
	v_mov_b32_e32 v213, v223
	ds_write_b64 v214, v[212:213] offset:5120
.LBB0_1210:
	s_or_b64 exec, exec, s[8:9]
	v_mul_f32_e32 v212, v15, v15
	v_mul_f32_e32 v213, v17, v17
	v_fmac_f32_e32 v212, v14, v14
	v_fmac_f32_e32 v213, v16, v16
	v_add_f32_e32 v212, v212, v213
	v_mul_f32_e32 v213, v11, v11
	v_mul_f32_e32 v214, v13, v13
	v_fmac_f32_e32 v213, v10, v10
	v_fmac_f32_e32 v214, v12, v12
	v_add_f32_e32 v213, v213, v214
	v_add_f32_e32 v212, v212, v213
	v_mul_f32_e32 v213, v7, v7
	v_mul_f32_e32 v214, v9, v9
	v_fmac_f32_e32 v213, v6, v6
	v_fmac_f32_e32 v214, v8, v8
	v_add_f32_e32 v213, v213, v214
	v_add_f32_e32 v212, v212, v213
	v_mul_f32_e32 v213, v3, v3
	v_mul_f32_e32 v214, v5, v5
	v_fmac_f32_e32 v213, v2, v2
	v_fmac_f32_e32 v214, v4, v4
	v_add_f32_e32 v213, v213, v214
	v_add_f32_e32 v212, v212, v213
	v_mov_b32_e32 v213, v212
	s_nop 1
	v_permlane16_swap_b32_e32 v213, v212
	s_waitcnt lgkmcnt(0)
	v_add_f32_e32 v212, v212, v213
	v_mov_b32_e32 v213, v212
	s_nop 1
	v_permlane32_swap_b32_e32 v213, v212
	s_and_saveexec_b64 s[8:9], s[6:7]
	s_cbranch_execz .LBB0_1212
	s_lshl_b32 s11, s83, 11
	s_add_i32 s11, s45, s11
	v_lshl_add_u32 v214, v219, 5, s11
	s_waitcnt lgkmcnt(0)
	v_add_f32_e32 v212, v212, v213
	v_mov_b32_e32 v213, v223
	ds_write_b64 v214, v[212:213] offset:5632

.LBB0_1343:
	s_or_b64 exec, exec, s[4:5]
	v_pk_mul_f32 v[164:165], v[56:57], v[140:141]
	v_pk_mul_f32 v[166:167], v[54:55], v[138:139]
	v_max_f32_e64 v164, |v164|, |v165|
	v_max_f32_e64 v166, |v166|, |v167|
	v_max3_f32 v168, v166, 0, v164
	v_pk_mul_f32 v[164:165], v[52:53], v[144:145]
	v_pk_mul_f32 v[166:167], v[50:51], v[142:143]
	v_max_f32_e64 v164, |v164|, |v165|
	v_max_f32_e64 v166, |v166|, |v167|
	v_max3_f32 v168, v168, v166, v164
	v_pk_mul_f32 v[164:165], v[68:69], v[136:137]
	v_pk_mul_f32 v[166:167], v[66:67], v[134:135]
	v_max_f32_e64 v164, |v164|, |v165|
	v_max_f32_e64 v166, |v166|, |v167|
	v_max3_f32 v168, v168, v166, v164
	v_pk_mul_f32 v[164:165], v[60:61], v[132:133]
	v_pk_mul_f32 v[166:167], v[58:59], v[130:131]
	v_max_f32_e64 v164, |v164|, |v165|
	v_max_f32_e64 v166, |v166|, |v167|
	v_max3_f32 v166, v168, v166, v164
	v_mul_f32_e32 v164, v55, v55
	v_mul_f32_e32 v165, v57, v57
	v_fmac_f32_e32 v164, v54, v54
	v_fmac_f32_e32 v165, v56, v56
	v_add_f32_e32 v164, v164, v165
	v_mul_f32_e32 v165, v51, v51
	v_mul_f32_e32 v167, v53, v53
	v_fmac_f32_e32 v165, v50, v50
	v_fmac_f32_e32 v167, v52, v52
	v_add_f32_e32 v165, v165, v167
	v_add_f32_e32 v164, v164, v165
	v_mul_f32_e32 v165, v67, v67
	v_mul_f32_e32 v167, v69, v69
	v_fmac_f32_e32 v165, v66, v66
	v_fmac_f32_e32 v167, v68, v68
	v_add_f32_e32 v165, v165, v167
	v_add_f32_e32 v164, v165, v164
	v_mul_f32_e32 v165, v59, v59
	v_mul_f32_e32 v167, v61, v61
	v_fmac_f32_e32 v165, v58, v58
	v_fmac_f32_e32 v167, v60, v60
	v_add_f32_e32 v165, v165, v167
	v_add_f32_e32 v164, v165, v164
	v_mov_b32_e32 v167, v166
	v_mov_b32_e32 v165, v164
	s_nop 1
	v_permlane16_swap_b32_e32 v167, v166
	v_permlane16_swap_b32_e32 v165, v164
	s_waitcnt lgkmcnt(1)
	v_max_f32_e32 v167, v167, v167
	s_waitcnt lgkmcnt(0)
	v_add_f32_e32 v164, v164, v165
	v_max_f32_e32 v166, v166, v167
	v_mov_b32_e32 v165, v164
	v_mov_b32_e32 v167, v166
	s_nop 1
	v_permlane32_swap_b32_e32 v165, v164
	v_permlane32_swap_b32_e32 v167, v166
	s_and_saveexec_b64 s[4:5], s[6:7]
	s_cbranch_execz .LBB0_1345
	s_lshl_b32 s16, s83, 11
	s_add_i32 s16, s45, s16
	s_waitcnt lgkmcnt(1)
	v_add_f32_e32 v164, v164, v165
	s_waitcnt lgkmcnt(0)
	v_max_f32_e32 v165, v167, v167
	v_max_f32_e32 v166, v166, v166
	v_lshl_add_u32 v168, v219, 5, s16
	v_max_f32_e32 v165, v166, v165
	ds_write_b64 v168, v[164:165] offset:512
.LBB0_1345:
	s_or_b64 exec, exec, s[4:5]
	v_pk_mul_f32 v[164:165], v[80:81], v[140:141]
	v_pk_mul_f32 v[166:167], v[78:79], v[138:139]
	v_max_f32_e64 v164, |v164|, |v165|
	v_max_f32_e64 v166, |v166|, |v167|
	v_max3_f32 v168, v166, 0, v164
	v_pk_mul_f32 v[164:165], v[76:77], v[144:145]
	v_pk_mul_f32 v[166:167], v[74:75], v[142:143]
	v_max_f32_e64 v164, |v164|, |v165|
	v_max_f32_e64 v166, |v166|, |v167|
	v_max3_f32 v168, v168, v166, v164
	v_pk_mul_f32 v[164:165], v[88:89], v[136:137]
	v_pk_mul_f32 v[166:167], v[86:87], v[134:135]
	v_max_f32_e64 v164, |v164|, |v165|
	v_max_f32_e64 v166, |v166|, |v167|
	v_max3_f32 v168, v168, v166, v164
	v_pk_mul_f32 v[164:165], v[84:85], v[132:133]
	v_pk_mul_f32 v[166:167], v[82:83], v[130:131]
	v_max_f32_e64 v164, |v164|, |v165|
	v_max_f32_e64 v166, |v166|, |v167|
	v_max3_f32 v166, v168, v166, v164
	v_mul_f32_e32 v164, v79, v79
	v_mul_f32_e32 v165, v81, v81
	v_fmac_f32_e32 v164, v78, v78
	v_fmac_f32_e32 v165, v80, v80
	v_add_f32_e32 v164, v164, v165
	v_mul_f32_e32 v165, v75, v75
	v_mul_f32_e32 v167, v77, v77
	v_fmac_f32_e32 v165, v74, v74
	v_fmac_f32_e32 v167, v76, v76
	v_add_f32_e32 v165, v165, v167
	v_add_f32_e32 v164, v164, v165
	v_mul_f32_e32 v165, v87, v87
	v_mul_f32_e32 v167, v89, v89
	v_fmac_f32_e32 v165, v86, v86
	v_fmac_f32_e32 v167, v88, v88
	v_add_f32_e32 v165, v165, v167
	v_add_f32_e32 v164, v165, v164
	v_mul_f32_e32 v165, v83, v83
	v_mul_f32_e32 v167, v85, v85
	v_fmac_f32_e32 v165, v82, v82
	v_fmac_f32_e32 v167, v84, v84
	v_add_f32_e32 v165, v165, v167
	v_add_f32_e32 v164, v165, v164
	v_mov_b32_e32 v167, v166
	v_mov_b32_e32 v165, v164
	s_nop 1
	v_permlane16_swap_b32_e32 v167, v166
	v_permlane16_swap_b32_e32 v165, v164
	s_waitcnt lgkmcnt(1)
	v_max_f32_e32 v167, v167, v167
	s_waitcnt lgkmcnt(0)
	v_add_f32_e32 v164, v164, v165
	v_max_f32_e32 v166, v166, v167
	v_mov_b32_e32 v165, v164
	v_mov_b32_e32 v167, v166
	s_nop 1
	v_permlane32_swap_b32_e32 v165, v164
	v_permlane32_swap_b32_e32 v167, v166
	s_and_saveexec_b64 s[4:5], s[6:7]
	s_cbranch_execz .LBB0_1347
	s_lshl_b32 s16, s83, 11
	s_add_i32 s16, s45, s16
	s_waitcnt lgkmcnt(1)
	v_add_f32_e32 v164, v164, v165
	s_waitcnt lgkmcnt(0)
	v_max_f32_e32 v165, v167, v167
	v_max_f32_e32 v166, v166, v166
	v_lshl_add_u32 v168, v219, 5, s16
	v_max_f32_e32 v165, v166, v165
	ds_write_b64 v168, v[164:165] offset:1024
.LBB0_1347:
	s_or_b64 exec, exec, s[4:5]
	v_pk_mul_f32 v[164:165], v[104:105], v[140:141]
	v_pk_mul_f32 v[166:167], v[102:103], v[138:139]
	v_max_f32_e64 v164, |v164|, |v165|
	v_max_f32_e64 v166, |v166|, |v167|
	v_max3_f32 v168, v166, 0, v164
	v_pk_mul_f32 v[164:165], v[96:97], v[144:145]
	v_pk_mul_f32 v[166:167], v[94:95], v[142:143]
	v_max_f32_e64 v164, |v164|, |v165|
	v_max_f32_e64 v166, |v166|, |v167|
	v_max3_f32 v168, v168, v166, v164
	v_pk_mul_f32 v[164:165], v[112:113], v[136:137]
	v_pk_mul_f32 v[166:167], v[110:111], v[134:135]
	v_max_f32_e64 v164, |v164|, |v165|
	v_max_f32_e64 v166, |v166|, |v167|
	v_max3_f32 v168, v168, v166, v164
	v_pk_mul_f32 v[164:165], v[108:109], v[132:133]
	v_pk_mul_f32 v[166:167], v[106:107], v[130:131]
	v_max_f32_e64 v164, |v164|, |v165|
	v_max_f32_e64 v166, |v166|, |v167|
	v_max3_f32 v166, v168, v166, v164
	v_mul_f32_e32 v164, v103, v103
	v_mul_f32_e32 v165, v105, v105
	v_fmac_f32_e32 v164, v102, v102
	v_fmac_f32_e32 v165, v104, v104
	v_add_f32_e32 v164, v164, v165
	v_mul_f32_e32 v165, v95, v95
	v_mul_f32_e32 v167, v97, v97
	v_fmac_f32_e32 v165, v94, v94
	v_fmac_f32_e32 v167, v96, v96
	v_add_f32_e32 v165, v165, v167
	v_add_f32_e32 v164, v164, v165
	v_mul_f32_e32 v165, v111, v111
	v_mul_f32_e32 v167, v113, v113
	v_fmac_f32_e32 v165, v110, v110
	v_fmac_f32_e32 v167, v112, v112
	v_add_f32_e32 v165, v165, v167
	v_add_f32_e32 v164, v165, v164
	v_mul_f32_e32 v165, v107, v107
	v_mul_f32_e32 v167, v109, v109
	v_fmac_f32_e32 v165, v106, v106
	v_fmac_f32_e32 v167, v108, v108
	v_add_f32_e32 v165, v165, v167
	v_add_f32_e32 v164, v165, v164
	v_mov_b32_e32 v167, v166
	v_mov_b32_e32 v165, v164
	s_nop 1
	v_permlane16_swap_b32_e32 v167, v166
	v_permlane16_swap_b32_e32 v165, v164
	s_waitcnt lgkmcnt(1)
	v_max_f32_e32 v167, v167, v167
	s_waitcnt lgkmcnt(0)
	v_add_f32_e32 v164, v164, v165
	v_max_f32_e32 v166, v166, v167
	v_mov_b32_e32 v165, v164
	v_mov_b32_e32 v167, v166
	s_nop 1
	v_permlane32_swap_b32_e32 v165, v164
	v_permlane32_swap_b32_e32 v167, v166
	s_and_saveexec_b64 s[4:5], s[6:7]
	s_cbranch_execz .LBB0_1349
	s_lshl_b32 s16, s83, 11
	s_add_i32 s16, s45, s16
	s_waitcnt lgkmcnt(1)
	v_add_f32_e32 v164, v164, v165
	s_waitcnt lgkmcnt(0)
	v_max_f32_e32 v165, v167, v167
	v_max_f32_e32 v166, v166, v166
	v_lshl_add_u32 v168, v219, 5, s16
	v_max_f32_e32 v165, v166, v165
	ds_write_b64 v168, v[164:165] offset:1536
.LBB0_1349:
	s_or_b64 exec, exec, s[4:5]
	v_pk_mul_f32 v[164:165], v[128:129], v[140:141]
	v_pk_mul_f32 v[166:167], v[126:127], v[138:139]
	v_max_f32_e64 v164, |v164|, |v165|
	v_max_f32_e64 v166, |v166|, |v167|
	v_max3_f32 v168, v166, 0, v164
	v_pk_mul_f32 v[164:165], v[120:121], v[144:145]
	v_pk_mul_f32 v[166:167], v[118:119], v[142:143]
	v_max_f32_e64 v164, |v164|, |v165|
	v_max_f32_e64 v166, |v166|, |v167|
	v_max3_f32 v168, v168, v166, v164
	v_pk_mul_f32 v[164:165], v[124:125], v[136:137]
	v_pk_mul_f32 v[166:167], v[122:123], v[134:135]
	v_max_f32_e64 v164, |v164|, |v165|
	v_max_f32_e64 v166, |v166|, |v167|
	v_max3_f32 v168, v168, v166, v164
	v_pk_mul_f32 v[164:165], v[116:117], v[132:133]
	v_pk_mul_f32 v[166:167], v[114:115], v[130:131]
	v_max_f32_e64 v164, |v164|, |v165|
	v_max_f32_e64 v166, |v166|, |v167|
	v_max3_f32 v166, v168, v166, v164
	v_mul_f32_e32 v164, v127, v127
	v_mul_f32_e32 v165, v129, v129
	v_fmac_f32_e32 v164, v126, v126
	v_fmac_f32_e32 v165, v128, v128
	v_add_f32_e32 v164, v164, v165
	v_mul_f32_e32 v165, v119, v119
	v_mul_f32_e32 v167, v121, v121
	v_fmac_f32_e32 v165, v118, v118
	v_fmac_f32_e32 v167, v120, v120
	v_add_f32_e32 v165, v165, v167
	v_add_f32_e32 v164, v164, v165
	v_mul_f32_e32 v165, v123, v123
	v_mul_f32_e32 v167, v125, v125
	v_fmac_f32_e32 v165, v122, v122
	v_fmac_f32_e32 v167, v124, v124
	v_add_f32_e32 v165, v165, v167
	v_add_f32_e32 v164, v165, v164
	v_mul_f32_e32 v165, v115, v115
	v_mul_f32_e32 v167, v117, v117
	v_fmac_f32_e32 v165, v114, v114
	v_fmac_f32_e32 v167, v116, v116
	v_add_f32_e32 v165, v165, v167
	v_add_f32_e32 v164, v165, v164
	v_mov_b32_e32 v167, v166
	v_mov_b32_e32 v165, v164
	s_nop 1
	v_permlane16_swap_b32_e32 v167, v166
	v_permlane16_swap_b32_e32 v165, v164
	s_waitcnt lgkmcnt(1)
	v_max_f32_e32 v167, v167, v167
	s_waitcnt lgkmcnt(0)
	v_add_f32_e32 v164, v164, v165
	v_max_f32_e32 v166, v166, v167
	v_mov_b32_e32 v165, v164
	v_mov_b32_e32 v167, v166
	s_nop 1
	v_permlane32_swap_b32_e32 v165, v164
	v_permlane32_swap_b32_e32 v167, v166
	s_and_saveexec_b64 s[4:5], s[6:7]
	s_cbranch_execz .LBB0_1351
	s_lshl_b32 s16, s83, 11
	s_add_i32 s16, s45, s16
	s_waitcnt lgkmcnt(1)
	v_add_f32_e32 v164, v164, v165
	s_waitcnt lgkmcnt(0)
	v_max_f32_e32 v165, v167, v167
	v_max_f32_e32 v166, v166, v166
	v_lshl_add_u32 v168, v219, 5, s16
	v_max_f32_e32 v165, v166, v165
	ds_write_b64 v168, v[164:165] offset:4096
.LBB0_1351:
	s_or_b64 exec, exec, s[4:5]
	v_pk_mul_f32 v[164:165], v[100:101], v[140:141]
	v_pk_mul_f32 v[166:167], v[98:99], v[138:139]
	v_max_f32_e64 v164, |v164|, |v165|
	v_max_f32_e64 v166, |v166|, |v167|
	v_max3_f32 v168, v166, 0, v164
	v_pk_mul_f32 v[164:165], v[92:93], v[144:145]
	v_pk_mul_f32 v[166:167], v[90:91], v[142:143]
	v_max_f32_e64 v164, |v164|, |v165|
	v_max_f32_e64 v166, |v166|, |v167|
	v_max3_f32 v168, v168, v166, v164
	v_pk_mul_f32 v[164:165], v[72:73], v[136:137]
	v_pk_mul_f32 v[166:167], v[70:71], v[134:135]
	v_max_f32_e64 v164, |v164|, |v165|
	v_max_f32_e64 v166, |v166|, |v167|
	v_max3_f32 v168, v168, v166, v164
	v_pk_mul_f32 v[164:165], v[64:65], v[132:133]
	v_pk_mul_f32 v[166:167], v[62:63], v[130:131]
	v_max_f32_e64 v164, |v164|, |v165|
	v_max_f32_e64 v166, |v166|, |v167|
	v_max3_f32 v166, v168, v166, v164
	v_mul_f32_e32 v164, v99, v99
	v_mul_f32_e32 v165, v101, v101
	v_fmac_f32_e32 v164, v98, v98
	v_fmac_f32_e32 v165, v100, v100
	v_add_f32_e32 v164, v164, v165
	v_mul_f32_e32 v165, v91, v91
	v_mul_f32_e32 v167, v93, v93
	v_fmac_f32_e32 v165, v90, v90
	v_fmac_f32_e32 v167, v92, v92
	v_add_f32_e32 v165, v165, v167
	v_add_f32_e32 v164, v164, v165
	v_mul_f32_e32 v165, v71, v71
	v_mul_f32_e32 v167, v73, v73
	v_fmac_f32_e32 v165, v70, v70
	v_fmac_f32_e32 v167, v72, v72
	v_add_f32_e32 v165, v165, v167
	v_add_f32_e32 v164, v165, v164
	v_mul_f32_e32 v165, v63, v63
	v_mul_f32_e32 v167, v65, v65
	v_fmac_f32_e32 v165, v62, v62
	v_fmac_f32_e32 v167, v64, v64
	v_add_f32_e32 v165, v165, v167
	v_add_f32_e32 v164, v165, v164
	v_mov_b32_e32 v167, v166
	v_mov_b32_e32 v165, v164
	s_nop 1
	v_permlane16_swap_b32_e32 v167, v166
	v_permlane16_swap_b32_e32 v165, v164
	s_waitcnt lgkmcnt(1)
	v_max_f32_e32 v167, v167, v167
	s_waitcnt lgkmcnt(0)
	v_add_f32_e32 v164, v164, v165
	v_max_f32_e32 v166, v166, v167
	v_mov_b32_e32 v165, v164
	v_mov_b32_e32 v167, v166
	s_nop 1
	v_permlane32_swap_b32_e32 v165, v164
	v_permlane32_swap_b32_e32 v167, v166
	s_and_saveexec_b64 s[4:5], s[6:7]
	s_cbranch_execz .LBB0_1353
	s_lshl_b32 s16, s83, 11
	s_add_i32 s16, s45, s16
	s_waitcnt lgkmcnt(1)
	v_add_f32_e32 v164, v164, v165
	s_waitcnt lgkmcnt(0)
	v_max_f32_e32 v165, v167, v167
	v_max_f32_e32 v166, v166, v166
	v_lshl_add_u32 v168, v219, 5, s16
	v_max_f32_e32 v165, v166, v165
	ds_write_b64 v168, v[164:165] offset:4608
.LBB0_1353:
	s_or_b64 exec, exec, s[4:5]
	v_pk_mul_f32 v[164:165], v[48:49], v[140:141]
	v_pk_mul_f32 v[166:167], v[46:47], v[138:139]
	v_max_f32_e64 v164, |v164|, |v165|
	v_max_f32_e64 v166, |v166|, |v167|
	v_max3_f32 v168, v166, 0, v164
	v_pk_mul_f32 v[164:165], v[40:41], v[144:145]
	v_pk_mul_f32 v[166:167], v[38:39], v[142:143]
	v_max_f32_e64 v164, |v164|, |v165|
	v_max_f32_e64 v166, |v166|, |v167|
	v_max3_f32 v168, v168, v166, v164
	v_pk_mul_f32 v[164:165], v[24:25], v[136:137]
	v_pk_mul_f32 v[166:167], v[22:23], v[134:135]
	v_max_f32_e64 v164, |v164|, |v165|
	v_max_f32_e64 v166, |v166|, |v167|
	v_max3_f32 v168, v168, v166, v164
	v_pk_mul_f32 v[164:165], v[20:21], v[132:133]
	v_pk_mul_f32 v[166:167], v[18:19], v[130:131]
	v_max_f32_e64 v164, |v164|, |v165|
	v_max_f32_e64 v166, |v166|, |v167|
	v_max3_f32 v166, v168, v166, v164
	v_mul_f32_e32 v164, v47, v47
	v_mul_f32_e32 v165, v49, v49
	v_fmac_f32_e32 v164, v46, v46
	v_fmac_f32_e32 v165, v48, v48
	v_add_f32_e32 v164, v164, v165
	v_mul_f32_e32 v165, v39, v39
	v_mul_f32_e32 v167, v41, v41
	v_fmac_f32_e32 v165, v38, v38
	v_fmac_f32_e32 v167, v40, v40
	v_add_f32_e32 v165, v165, v167
	v_add_f32_e32 v164, v164, v165
	v_mul_f32_e32 v165, v23, v23
	v_mul_f32_e32 v167, v25, v25
	v_fmac_f32_e32 v165, v22, v22
	v_fmac_f32_e32 v167, v24, v24
	v_add_f32_e32 v165, v165, v167
	v_add_f32_e32 v164, v165, v164
	v_mul_f32_e32 v165, v19, v19
	v_mul_f32_e32 v167, v21, v21
	v_fmac_f32_e32 v165, v18, v18
	v_fmac_f32_e32 v167, v20, v20
	v_add_f32_e32 v165, v165, v167
	v_add_f32_e32 v164, v165, v164
	v_mov_b32_e32 v167, v166
	v_mov_b32_e32 v165, v164
	s_nop 1
	v_permlane16_swap_b32_e32 v167, v166
	v_permlane16_swap_b32_e32 v165, v164
	s_waitcnt lgkmcnt(1)
	v_max_f32_e32 v167, v167, v167
	s_waitcnt lgkmcnt(0)
	v_add_f32_e32 v164, v164, v165
	v_max_f32_e32 v166, v166, v167
	v_mov_b32_e32 v165, v164
	v_mov_b32_e32 v167, v166
	s_nop 1
	v_permlane32_swap_b32_e32 v165, v164
	v_permlane32_swap_b32_e32 v167, v166
	s_and_saveexec_b64 s[4:5], s[6:7]
	s_cbranch_execz .LBB0_1355
	s_lshl_b32 s16, s83, 11
	s_add_i32 s16, s45, s16
	s_waitcnt lgkmcnt(1)
	v_add_f32_e32 v164, v164, v165
	s_waitcnt lgkmcnt(0)
	v_max_f32_e32 v165, v167, v167
	v_max_f32_e32 v166, v166, v166
	v_lshl_add_u32 v168, v219, 5, s16
	v_max_f32_e32 v165, v166, v165
	ds_write_b64 v168, v[164:165] offset:5120
.LBB0_1355:
	s_or_b64 exec, exec, s[4:5]
	v_pk_mul_f32 v[164:165], v[16:17], v[140:141]
	v_pk_mul_f32 v[166:167], v[14:15], v[138:139]
	v_max_f32_e64 v164, |v164|, |v165|
	v_max_f32_e64 v166, |v166|, |v167|
	v_max3_f32 v168, v166, 0, v164
	v_pk_mul_f32 v[164:165], v[12:13], v[144:145]
	v_pk_mul_f32 v[166:167], v[10:11], v[142:143]
	v_max_f32_e64 v164, |v164|, |v165|
	v_max_f32_e64 v166, |v166|, |v167|
	v_max3_f32 v168, v168, v166, v164
	v_pk_mul_f32 v[164:165], v[8:9], v[136:137]
	v_pk_mul_f32 v[166:167], v[6:7], v[134:135]
	v_max_f32_e64 v164, |v164|, |v165|
	v_max_f32_e64 v166, |v166|, |v167|
	v_max3_f32 v168, v168, v166, v164
	v_pk_mul_f32 v[164:165], v[4:5], v[132:133]
	v_pk_mul_f32 v[166:167], v[2:3], v[130:131]
	v_max_f32_e64 v164, |v164|, |v165|
	v_max_f32_e64 v166, |v166|, |v167|
	v_max3_f32 v166, v168, v166, v164
	v_mul_f32_e32 v164, v15, v15
	v_mul_f32_e32 v165, v17, v17
	v_fmac_f32_e32 v164, v14, v14
	v_fmac_f32_e32 v165, v16, v16
	v_add_f32_e32 v164, v164, v165
	v_mul_f32_e32 v165, v11, v11
	v_mul_f32_e32 v167, v13, v13
	v_fmac_f32_e32 v165, v10, v10
	v_fmac_f32_e32 v167, v12, v12
	v_add_f32_e32 v165, v165, v167
	v_add_f32_e32 v164, v164, v165
	v_mul_f32_e32 v165, v7, v7
	v_mul_f32_e32 v167, v9, v9
	v_fmac_f32_e32 v165, v6, v6
	v_fmac_f32_e32 v167, v8, v8
	v_add_f32_e32 v165, v165, v167
	v_add_f32_e32 v164, v165, v164
	v_mul_f32_e32 v165, v3, v3
	v_mul_f32_e32 v167, v5, v5
	v_fmac_f32_e32 v165, v2, v2
	v_fmac_f32_e32 v167, v4, v4
	v_add_f32_e32 v165, v165, v167
	v_add_f32_e32 v164, v165, v164
	v_mov_b32_e32 v167, v166
	v_mov_b32_e32 v165, v164
	s_nop 1
	v_permlane16_swap_b32_e32 v167, v166
	v_permlane16_swap_b32_e32 v165, v164
	s_waitcnt lgkmcnt(1)
	v_max_f32_e32 v167, v167, v167
	s_waitcnt lgkmcnt(0)
	v_add_f32_e32 v164, v164, v165
	v_max_f32_e32 v166, v166, v167
	v_mov_b32_e32 v165, v164
	v_mov_b32_e32 v167, v166
	s_nop 1
	v_permlane32_swap_b32_e32 v165, v164
	v_permlane32_swap_b32_e32 v167, v166
	s_and_saveexec_b64 s[4:5], s[6:7]
	s_cbranch_execz .LBB0_1357
	s_lshl_b32 s6, s83, 11
	s_add_i32 s45, s45, s6
	s_waitcnt lgkmcnt(1)
	v_add_f32_e32 v164, v164, v165
	s_waitcnt lgkmcnt(0)
	v_max_f32_e32 v165, v167, v167
	v_max_f32_e32 v166, v166, v166
	v_lshl_add_u32 v168, v219, 5, s45
	v_max_f32_e32 v165, v166, v165
	ds_write_b64 v168, v[164:165] offset:5632
